# v32 plus: attention row-sum adds moved under the PV MFMAs; prep q/k norm reductions use DPP row ops for the last 4 butterfly hops
# speedup vs baseline: 1.0064x; 1.0064x over previous
; #define MFMA(a, b, c) __builtin_amdgcn_mfma_f32_32x32x16_bf16((a), (b), (c), 0, 0, 0)
; DI void attn_item(const Params& p, int seq, int hd, int qblk, char* smem, int tid_) {
;     ...
;     float ps = 0.f;
; #pragma unroll
;     for (int kb2 = 0; kb2 < 2; kb2++)
; #pragma unroll
;       for (int i = 0; i < 16; i++) {
;         float pv = __builtin_amdgcn_exp2f(st[kb2][i] - m);
;         st[kb2][i] = pv;
;         ps += pv;
;       }
;     lsum += ps;
;     __builtin_amdgcn_sched_barrier(0);
; #pragma unroll
;     for (int g = 0; g < 16; g++) {
;       const int kb2 = g >> 3, c = (g >> 2) & 1;
;       unsigned pk[4];
; #pragma unroll
;       for (int j = 0; j < 4; j++) pk[j] = pack2(st[kb2][8 * c + 2 * j], st[kb2][8 * c + 2 * j + 1]);
;       u32x4 pu = {pk[0], pk[1], pk[2], pk[3]};
;       bf16x8 pf = __builtin_bit_cast(bf16x8, pu);
;       o[g & 3] = MFMA(vfr[g & 3], pf, o[g & 3]);
;       if (g + 4 < 16) vfr[g & 3] = VFRAG(g + 4);
;       __builtin_amdgcn_sched_barrier(0);
;     }
;     ...
;     if (kt + 1 < 32) {
;       u16* sKn = (u16*)(smem + ((kt + 1) & 1) * 45056);
;       u16* sVn = sKn + 64 * 200;
; #pragma unroll
;       for (int i = 0; i < 3; i++) *(u32x4*)(sKn + kl + 64 * i) = rk[i];
; #pragma unroll
;       for (int i = 0; i < 2; i++) *(u32x4*)(sVn + vl + 64 * i * 72) = rv[i];
;     }
;     __syncthreads();
;     if (kt + 2 < 32) {
; #pragma unroll
;       for (int i = 0; i < 3; i++) rk[i] = *(const u32x4*)(kg + (size_t)(kt + 2) * 64 * 768 + 64 * i);
; #pragma unroll
;       for (int i = 0; i < 2; i++) rv[i] = *(const u32x4*)(vg + (size_t)(64 * i) * 2048 + (kt + 2) * 64);
;     }
.LBB0_627:
	v_sub_f32_e32 v64, v64, v198
	v_sub_f32_e32 v65, v65, v198
	v_sub_f32_e32 v66, v66, v198
	v_sub_f32_e32 v67, v67, v198
	v_sub_f32_e32 v68, v68, v198
	v_sub_f32_e32 v69, v69, v198
	v_sub_f32_e32 v70, v70, v198
	v_sub_f32_e32 v71, v71, v198
	v_sub_f32_e32 v72, v72, v198
	v_sub_f32_e32 v73, v73, v198
	v_sub_f32_e32 v74, v74, v198
	v_sub_f32_e32 v75, v75, v198
	v_sub_f32_e32 v76, v76, v198
	v_sub_f32_e32 v77, v77, v198
	v_sub_f32_e32 v78, v78, v198
	v_sub_f32_e32 v79, v79, v198
	v_sub_f32_e32 v80, v80, v198
	v_sub_f32_e32 v81, v81, v198
	v_sub_f32_e32 v82, v82, v198
	v_sub_f32_e32 v83, v83, v198
	v_sub_f32_e32 v84, v84, v198
	v_sub_f32_e32 v85, v85, v198
	v_sub_f32_e32 v86, v86, v198
	v_sub_f32_e32 v87, v87, v198
	v_sub_f32_e32 v88, v88, v198
	v_sub_f32_e32 v89, v89, v198
	v_sub_f32_e32 v90, v90, v198
	v_sub_f32_e32 v91, v91, v198
	v_sub_f32_e32 v92, v92, v198
	v_sub_f32_e32 v93, v93, v198
	v_sub_f32_e32 v94, v94, v198
	v_sub_f32_e32 v95, v95, v198
	v_exp_f32_e32 v64, v64
	v_exp_f32_e32 v65, v65
	v_exp_f32_e32 v66, v66
	v_exp_f32_e32 v67, v67
	v_exp_f32_e32 v68, v68
	v_exp_f32_e32 v69, v69
	v_exp_f32_e32 v70, v70
	v_exp_f32_e32 v71, v71
	v_exp_f32_e32 v72, v72
	v_exp_f32_e32 v73, v73
	v_exp_f32_e32 v74, v74
	v_exp_f32_e32 v75, v75
	v_exp_f32_e32 v76, v76
	v_exp_f32_e32 v77, v77
	v_exp_f32_e32 v78, v78
	v_exp_f32_e32 v79, v79
	v_exp_f32_e32 v80, v80
	v_exp_f32_e32 v81, v81
	v_exp_f32_e32 v82, v82
	v_exp_f32_e32 v83, v83
	v_exp_f32_e32 v84, v84
	v_exp_f32_e32 v85, v85
	v_exp_f32_e32 v86, v86
	v_exp_f32_e32 v87, v87
	v_exp_f32_e32 v88, v88
	v_exp_f32_e32 v89, v89
	v_exp_f32_e32 v90, v90
	v_exp_f32_e32 v91, v91
	v_exp_f32_e32 v92, v92
	v_exp_f32_e32 v93, v93
	v_exp_f32_e32 v94, v94
	v_exp_f32_e32 v95, v95
	v_cvt_pk_bf16_f32 v200, v64, v65
	v_cvt_pk_bf16_f32 v201, v66, v67
	v_cvt_pk_bf16_f32 v202, v68, v69
	v_cvt_pk_bf16_f32 v203, v70, v71
	v_add3_u32 v199, s5, v195, v188
	s_waitcnt lgkmcnt(3)
	v_mfma_f32_32x32x16_bf16 v[48:63], v[176:179], v[200:203], v[48:63]
	v_add_f32_e32 v64, 0, v64
	v_add_f32_e32 v64, v65, v64
	ds_read_b128 v[176:179], v199 offset:25632
	s_waitcnt lgkmcnt(3)
	v_mfma_f32_32x32x16_bf16 v[32:47], v[172:175], v[200:203], v[32:47]
	v_add_f32_e32 v64, v66, v64
	v_add_f32_e32 v64, v67, v64
	ds_read_b128 v[172:175], v199 offset:30240
	s_waitcnt lgkmcnt(3)
	v_mfma_f32_32x32x16_bf16 v[16:31], v[168:171], v[200:203], v[16:31]
	v_add_f32_e32 v64, v68, v64
	v_add_f32_e32 v64, v69, v64
	ds_read_b128 v[168:171], v199 offset:34848
	s_waitcnt lgkmcnt(3)
	v_mfma_f32_32x32x16_bf16 v[0:15], v[164:167], v[200:203], v[0:15]
	v_add_f32_e32 v64, v70, v64
	v_add_f32_e32 v64, v71, v64
	ds_read_b128 v[164:167], v199 offset:39456
	v_cvt_pk_bf16_f32 v200, v72, v73
	v_cvt_pk_bf16_f32 v201, v74, v75
	v_cvt_pk_bf16_f32 v202, v76, v77
	v_cvt_pk_bf16_f32 v203, v78, v79
	s_waitcnt lgkmcnt(3)
	s_nop 0
	v_mfma_f32_32x32x16_bf16 v[48:63], v[176:179], v[200:203], v[48:63]
	v_add_f32_e32 v64, v72, v64
	v_add_f32_e32 v64, v73, v64
	ds_read_b128 v[176:179], v199 offset:25664
	s_waitcnt lgkmcnt(3)
	v_mfma_f32_32x32x16_bf16 v[32:47], v[172:175], v[200:203], v[32:47]
	v_add_f32_e32 v64, v74, v64
	v_add_f32_e32 v64, v75, v64
	ds_read_b128 v[172:175], v199 offset:30272
	s_waitcnt lgkmcnt(3)
	v_mfma_f32_32x32x16_bf16 v[16:31], v[168:171], v[200:203], v[16:31]
	v_add_f32_e32 v64, v76, v64
	v_add_f32_e32 v64, v77, v64
	ds_read_b128 v[168:171], v199 offset:34880
	s_waitcnt lgkmcnt(3)
	v_mfma_f32_32x32x16_bf16 v[0:15], v[164:167], v[200:203], v[0:15]
	v_add_f32_e32 v64, v78, v64
	v_add_f32_e32 v64, v79, v64
	ds_read_b128 v[164:167], v199 offset:39488
	v_cvt_pk_bf16_f32 v200, v80, v81
	v_cvt_pk_bf16_f32 v201, v82, v83
	v_cvt_pk_bf16_f32 v202, v84, v85
	v_cvt_pk_bf16_f32 v203, v86, v87
	s_waitcnt lgkmcnt(3)
	s_nop 0
	v_mfma_f32_32x32x16_bf16 v[48:63], v[176:179], v[200:203], v[48:63]
	v_add_f32_e32 v64, v80, v64
	v_add_f32_e32 v64, v81, v64
	ds_read_b128 v[176:179], v199 offset:25696
	s_waitcnt lgkmcnt(3)
	v_mfma_f32_32x32x16_bf16 v[32:47], v[172:175], v[200:203], v[32:47]
	v_add_f32_e32 v64, v82, v64
	v_add_f32_e32 v64, v83, v64
	ds_read_b128 v[172:175], v199 offset:30304
	s_waitcnt lgkmcnt(3)
	v_mfma_f32_32x32x16_bf16 v[16:31], v[168:171], v[200:203], v[16:31]
	v_add_f32_e32 v64, v84, v64
	v_add_f32_e32 v64, v85, v64
	ds_read_b128 v[168:171], v199 offset:34912
	s_waitcnt lgkmcnt(3)
	v_mfma_f32_32x32x16_bf16 v[0:15], v[164:167], v[200:203], v[0:15]
	v_add_f32_e32 v64, v86, v64
	v_add_f32_e32 v64, v87, v64
	ds_read_b128 v[164:167], v199 offset:39520
	v_cvt_pk_bf16_f32 v200, v88, v89
	v_cvt_pk_bf16_f32 v201, v90, v91
	v_cvt_pk_bf16_f32 v202, v92, v93
	v_cvt_pk_bf16_f32 v203, v94, v95
	s_waitcnt lgkmcnt(3)
	s_nop 0
	v_mfma_f32_32x32x16_bf16 v[48:63], v[176:179], v[200:203], v[48:63]
	v_add_f32_e32 v64, v88, v64
	v_add_f32_e32 v64, v89, v64
	s_waitcnt lgkmcnt(2)
	v_mfma_f32_32x32x16_bf16 v[32:47], v[172:175], v[200:203], v[32:47]
	v_add_f32_e32 v64, v90, v64
	v_add_f32_e32 v64, v91, v64
	s_waitcnt lgkmcnt(1)
	v_mfma_f32_32x32x16_bf16 v[16:31], v[168:171], v[200:203], v[16:31]
	v_add_f32_e32 v64, v92, v64
	v_add_f32_e32 v64, v93, v64
	s_waitcnt lgkmcnt(0)
	v_mfma_f32_32x32x16_bf16 v[0:15], v[164:167], v[200:203], v[0:15]
	v_add_f32_e32 v64, v94, v64
	v_add_f32_e32 v64, v95, v64
	s_add_i32 s5, s3, 1
	s_bitcmp1_b32 s5, 0
	s_cselect_b32 s1, 0xb000, 0
	s_add_i32 s1, s1, 0
	v_lshl_add_u32 v164, v182, 1, s1
	s_waitcnt vmcnt(4)
	ds_write_b128 v164, v[144:147]
	s_waitcnt vmcnt(3)
	ds_write_b128 v164, v[148:151] offset:128
	s_waitcnt vmcnt(2)
	ds_write_b128 v164, v[152:155] offset:256
	v_lshl_add_u32 v164, v196, 1, s1
	s_cmp_gt_u32 s3, 29
	s_waitcnt vmcnt(1)
	ds_write_b128 v164, v[156:159] offset:25600
	s_waitcnt vmcnt(0)
	ds_write_b128 v164, v[160:163] offset:34816
	s_waitcnt lgkmcnt(0)
	s_barrier
	s_cbranch_scc1 .LBB0_629
	global_load_dwordx4 v[144:147], v[186:187], off offset:-128
	global_load_dwordx4 v[148:151], v[186:187], off
	global_load_dwordx4 v[152:155], v[186:187], off offset:128
	global_load_dwordx4 v[156:159], v[184:185], off
	v_add_co_u32_e32 v160, vcc, 0x40000, v184
	s_nop 1
	v_addc_co_u32_e32 v161, vcc, 0, v185, vcc
	global_load_dwordx4 v[160:163], v[160:161], off
.LBB0_629:
	s_mov_b64 s[6:7], 0x18000
	v_add_f32_e32 v194, v194, v64
	v_lshl_add_u64 v[184:185], v[184:185], 0, s[14:15]
	s_cmp_lg_u32 s5, 31
	v_lshl_add_u64 v[186:187], v[186:187], 0, s[6:7]
	s_cbranch_scc0 .LBB0_631
	v_mov_b32_e32 v199, v198
	s_mov_b32 s3, s5
	s_branch .LBB0_624

; DI u16 f2bf(float a) { return (u16)(pack2(a, 0.f) & 0xffffu); }
; DI float bf2f(u16 v) { return __uint_as_float(((unsigned)v) << 16); }
; DI float wave_sum(float v) {
; #pragma unroll
;   for (int o = 32; o; o >>= 1) v += __shfl_xor(v, o);
;   return v;
; DI void prep_item(const Params& p, int l, int item) {
;     ...
;       for (int j = 0; j < 4; j++) {
;         const size_t t = tb + t4 + j;
;         csa[j] = rope[(s0 + t4 + j) * 32 + (lane & 31)];
;         const u16* qr = qb + t * 768 + hd * 192;
;         qa[j][0] = qr[lane]; qa[j][1] = qr[64 + lane]; qa[j][2] = qr[128 + lane];
;         const u16* kvr = kvraw + t * 1024 + hd * 256;
;         ka[j][0] = kvr[lane]; ka[j][1] = kvr[64 + lane]; ka[j][2] = z[t * 1760 + 896 + lane];
;         vv[t4 + j] = *(const unsigned*)(kvr + 128 + 2 * lane);
;       }
; #pragma unroll
;       for (int j = 0; j < 4; j++) {
;         const size_t t = tb + t4 + j;
;         const float2 cs = csa[j];
;         u16* qr = qb + t * 768 + hd * 192;
;         float q0 = bf2f(qa[j][0]), q1 = bf2f(qa[j][1]), q2 = bf2f(qa[j][2]);
;         float ss = wave_sum(q0 * q0 + q1 * q1 + q2 * q2);
;         float rs = rsqrtf(ss * (1.f / 192.f) + EPS);
;         q0 *= rs * gq0; q1 *= rs * gq1; q2 *= rs * gq2;
;         float pr = __shfl_xor(q2, 32);
;         float rot = (lane < 32) ? (q2 * cs.x - pr * cs.y) : (q2 * cs.x + pr * cs.y);
;         qr[lane] = f2bf(q0 * QS); qr[64 + lane] = f2bf(q1 * QS); qr[128 + lane] = f2bf(rot * QS);
;         float k0 = bf2f(ka[j][0]), k1 = bf2f(ka[j][1]), k2 = bf2f(ka[j][2]);
;         float ks = wave_sum(k0 * k0 + k1 * k1 + k2 * k2);
;         float rk = rsqrtf(ks * (1.f / 192.f) + EPS);
;         k0 *= rk * gk0; k1 *= rk * gk1; k2 *= rk * gk2;
;         float pk = __shfl_xor(k2, 32);
;         float rotk = (lane < 32) ? (k2 * cs.x - pk * cs.y) : (k2 * cs.x + pk * cs.y);
;         u16* kr = kb + t * 768 + hd * 192;
;         kr[lane] = f2bf(k0); kr[64 + lane] = f2bf(k1); kr[128 + lane] = f2bf(rotk);
;       }
.LBB0_667:
	s_mul_i32 s88, s23, 0xc0
	s_lshl_b64 s[2:3], s[88:89], 1
	s_add_u32 s28, s84, s2
	s_addc_u32 s29, s85, s3
	s_lshl_b32 s1, s23, 9
	s_add_u32 s26, s90, s1
	s_addc_u32 s27, s91, 0
	v_lshl_add_u64 v[66:67], s[28:29], 0, v[2:3]
	v_lshl_add_u64 v[82:83], v[66:67], 0, v[188:189]
	v_lshl_add_u64 v[66:67], s[26:27], 0, v[4:5]
	v_mov_b32_e32 v65, v189
	v_lshl_add_u64 v[88:89], v[66:67], 0, v[188:189]
	v_lshl_add_u64 v[66:67], v[66:67], 0, v[64:65]
	global_load_dwordx2 v[80:81], v[0:1], off
	global_load_dword v109, v[66:67], off offset:256
	global_load_dwordx2 v[78:79], v[0:1], off offset:256
	v_lshl_add_u64 v[66:67], s[26:27], 0, v[8:9]
	v_lshl_add_u64 v[94:95], v[66:67], 0, v[188:189]
	v_lshl_add_u64 v[66:67], v[66:67], 0, v[64:65]
	global_load_dword v110, v[66:67], off offset:256
	global_load_dwordx2 v[74:75], v[0:1], off offset:512
	v_lshl_add_u64 v[66:67], s[26:27], 0, v[10:11]
	v_lshl_add_u64 v[90:91], v[66:67], 0, v[188:189]
	v_lshl_add_u64 v[66:67], v[66:67], 0, v[64:65]
	global_load_dword v111, v[66:67], off offset:256
	global_load_dwordx2 v[72:73], v[0:1], off offset:768
	v_lshl_add_u64 v[66:67], s[26:27], 0, v[14:15]
	v_lshl_add_u64 v[92:93], v[66:67], 0, v[188:189]
	v_lshl_add_u64 v[66:67], v[66:67], 0, v[64:65]
	global_load_dword v112, v[66:67], off offset:256
	global_load_ushort v76, v[82:83], off offset:256
	global_load_ushort v77, v[82:83], off
	v_lshl_add_u64 v[66:67], v[16:17], 1, s[28:29]
	v_lshl_add_u64 v[84:85], v[82:83], 0, s[70:71]
	v_lshl_add_u64 v[70:71], v[82:83], 0, s[68:69]
	v_lshl_add_u64 v[68:69], v[84:85], 0, s[68:69]
	s_waitcnt vmcnt(1)
	v_lshlrev_b32_e32 v114, 16, v76
	s_waitcnt vmcnt(0)
	v_lshlrev_b32_e32 v115, 16, v77
	v_lshl_add_u64 v[76:77], v[66:67], 0, v[188:189]
	global_load_ushort v66, v[82:83], off offset:128
	global_load_ushort v67, v[88:89], off offset:128
	v_pk_mul_f32 v[116:117], v[114:115], v[114:115]
	s_waitcnt vmcnt(1)
	v_lshlrev_b32_e32 v87, 16, v66
	s_waitcnt vmcnt(0)
	v_lshlrev_b32_e32 v86, 16, v67
	global_load_ushort v66, v[88:89], off
	global_load_ushort v67, v[6:7], off
	v_mov_b32_e32 v119, v117
	s_waitcnt vmcnt(1)
	v_lshlrev_b32_e32 v89, 16, v66
	s_waitcnt vmcnt(0)
	v_lshlrev_b32_e32 v88, 16, v67
	v_pk_mul_f32 v[66:67], v[88:89], v[88:89]
	s_nop 0
	v_mov_b32_e32 v118, v67
	v_pk_fma_f32 v[118:119], v[86:87], v[86:87], v[118:119]
	v_mov_b32_e32 v67, v116
	v_pk_add_f32 v[66:67], v[66:67], v[118:119]
	ds_bpermute_b32 v117, v102, v67
	ds_bpermute_b32 v116, v102, v66
	s_waitcnt lgkmcnt(0)
	v_pk_add_f32 v[66:67], v[66:67], v[116:117]
	ds_bpermute_b32 v117, v103, v67
	ds_bpermute_b32 v116, v103, v66
	s_waitcnt lgkmcnt(0)
	v_pk_add_f32 v[66:67], v[66:67], v[116:117]
	s_waitcnt lgkmcnt(0)
	s_nop 1
	v_add_f32_dpp v66, v66, v66 row_mirror row_mask:0xf bank_mask:0xf
	v_add_f32_dpp v67, v67, v67 row_mirror row_mask:0xf bank_mask:0xf
	s_waitcnt lgkmcnt(0)
	s_nop 1
	v_add_f32_dpp v66, v66, v66 row_half_mirror row_mask:0xf bank_mask:0xf
	v_add_f32_dpp v67, v67, v67 row_half_mirror row_mask:0xf bank_mask:0xf
	s_waitcnt lgkmcnt(0)
	s_nop 1
	v_add_f32_dpp v66, v66, v66 quad_perm:[2,3,0,1] row_mask:0xf bank_mask:0xf
	v_add_f32_dpp v67, v67, v67 quad_perm:[2,3,0,1] row_mask:0xf bank_mask:0xf
	s_waitcnt lgkmcnt(0)
	s_nop 1
	v_add_f32_dpp v116, v66, v66 quad_perm:[1,0,3,2] row_mask:0xf bank_mask:0xf
	v_add_f32_dpp v117, v67, v67 quad_perm:[1,0,3,2] row_mask:0xf bank_mask:0xf
	v_mov_b64_e32 v[66:67], s[10:11]
	v_pk_fma_f32 v[116:117], v[116:117], s[0:1], v[66:67] op_sel_hi:[1,0,0]
	s_nop 0
	v_mul_f32_e32 v113, 0x4b800000, v117
	v_cmp_gt_f32_e64 s[38:39], s33, v117
	v_cmp_gt_f32_e64 s[36:37], s33, v116
	s_nop 0
	v_cndmask_b32_e64 v113, v117, v113, s[38:39]
	v_rsq_f32_e32 v113, v113
	s_nop 0
	v_mul_f32_e32 v117, 0x45800000, v113
	v_cndmask_b32_e64 v113, v113, v117, s[38:39]
	v_mul_f32_e32 v117, v96, v113
	v_mul_f32_e32 v115, v117, v115
	v_mul_f32_e32 v117, v97, v113
	v_mul_f32_e32 v113, v98, v113
	v_mul_f32_e32 v113, v113, v114
	ds_bpermute_b32 v114, v102, v113
	v_mul_f32_e32 v87, v117, v87
	s_waitcnt lgkmcnt(0)
	v_mul_f32_e32 v114, v81, v114
	v_cndmask_b32_e64 v114, v114, -v114, vcc
	v_fmac_f32_e32 v114, v80, v113
	v_mul_f32_e32 v113, 0x3dd53b94, v115
	global_load_ushort v115, v[82:83], off offset:1792
	global_load_ushort v117, v[82:83], off offset:1536
	global_load_ushort v118, v[82:83], off offset:1664
	global_load_ushort v119, v[94:95], off offset:128
	s_nop 0
	global_load_ushort v94, v[94:95], off
	s_nop 0
	global_load_ushort v95, v[6:7], off offset:3520
	global_load_ushort v120, v[82:83], off offset:3328
	global_load_ushort v121, v[82:83], off offset:3072
	global_load_ushort v122, v[82:83], off offset:3200
	global_load_ushort v123, v[90:91], off offset:128
	global_load_ushort v124, v[90:91], off
	global_load_ushort v125, v[12:13], off
	global_load_ushort v126, v[84:85], off offset:3328
	global_load_ushort v127, v[84:85], off offset:3072
	global_load_ushort v128, v[84:85], off offset:3200
	global_load_ushort v129, v[92:93], off offset:128
	global_load_ushort v130, v[92:93], off
	global_load_ushort v131, v[12:13], off offset:3520
	v_mul_f32_e32 v82, 0x3dd53b94, v87
	v_cvt_pk_bf16_f32 v82, v82, s0
	global_store_short v[76:77], v82, off offset:128
	v_mul_f32_e32 v82, 0x3dd53b94, v114
	v_cvt_pk_bf16_f32 v82, v82, s0
	global_store_short v[76:77], v82, off offset:256
	v_mul_f32_e32 v82, 0x4b800000, v116
	v_cndmask_b32_e64 v82, v116, v82, s[36:37]
	v_rsq_f32_e32 v82, v82
	v_cvt_pk_bf16_f32 v113, v113, s0
	global_store_short v[76:77], v113, off
	v_mul_f32_e32 v83, 0x45800000, v82
	v_cndmask_b32_e64 v82, v82, v83, s[36:37]
	v_mul_f32_e32 v83, v99, v82
	v_mul_f32_e32 v84, v100, v82
	v_mul_f32_e32 v82, v101, v82
	v_mul_f32_e32 v82, v82, v88
	ds_bpermute_b32 v85, v102, v82
	v_mul_f32_e32 v83, v83, v89
	v_mul_f32_e32 v84, v84, v86
	v_lshl_add_u64 v[86:87], v[76:77], 0, s[70:71]
	s_waitcnt lgkmcnt(0)
; DI u16 f2bf(float a) { return (u16)(pack2(a, 0.f) & 0xffffu); }
; DI float bf2f(u16 v) { return __uint_as_float(((unsigned)v) << 16); }
; DI float wave_sum(float v) {
; #pragma unroll
;   for (int o = 32; o; o >>= 1) v += __shfl_xor(v, o);
;   return v;
; DI void prep_item(const Params& p, int l, int item) {
;     ...
;       for (int j = 0; j < 4; j++) {
;         const size_t t = tb + t4 + j;
;         csa[j] = rope[(s0 + t4 + j) * 32 + (lane & 31)];
;         const u16* qr = qb + t * 768 + hd * 192;
;         qa[j][0] = qr[lane]; qa[j][1] = qr[64 + lane]; qa[j][2] = qr[128 + lane];
;         const u16* kvr = kvraw + t * 1024 + hd * 256;
;         ka[j][0] = kvr[lane]; ka[j][1] = kvr[64 + lane]; ka[j][2] = z[t * 1760 + 896 + lane];
;         vv[t4 + j] = *(const unsigned*)(kvr + 128 + 2 * lane);
;       }
; #pragma unroll
;       for (int j = 0; j < 4; j++) {
;         const size_t t = tb + t4 + j;
;         const float2 cs = csa[j];
;         u16* qr = qb + t * 768 + hd * 192;
;         float q0 = bf2f(qa[j][0]), q1 = bf2f(qa[j][1]), q2 = bf2f(qa[j][2]);
;         float ss = wave_sum(q0 * q0 + q1 * q1 + q2 * q2);
;         float rs = rsqrtf(ss * (1.f / 192.f) + EPS);
;         q0 *= rs * gq0; q1 *= rs * gq1; q2 *= rs * gq2;
;         float pr = __shfl_xor(q2, 32);
;         float rot = (lane < 32) ? (q2 * cs.x - pr * cs.y) : (q2 * cs.x + pr * cs.y);
;         qr[lane] = f2bf(q0 * QS); qr[64 + lane] = f2bf(q1 * QS); qr[128 + lane] = f2bf(rot * QS);
;         float k0 = bf2f(ka[j][0]), k1 = bf2f(ka[j][1]), k2 = bf2f(ka[j][2]);
;         float ks = wave_sum(k0 * k0 + k1 * k1 + k2 * k2);
;         float rk = rsqrtf(ks * (1.f / 192.f) + EPS);
;         k0 *= rk * gk0; k1 *= rk * gk1; k2 *= rk * gk2;
;         float pk = __shfl_xor(k2, 32);
;         float rotk = (lane < 32) ? (k2 * cs.x - pk * cs.y) : (k2 * cs.x + pk * cs.y);
;         u16* kr = kb + t * 768 + hd * 192;
;         kr[lane] = f2bf(k0); kr[64 + lane] = f2bf(k1); kr[128 + lane] = f2bf(rotk);
;       }
	v_mul_f32_e32 v81, v81, v85
	v_cndmask_b32_e64 v85, v81, -v81, vcc
	v_fmac_f32_e32 v85, v80, v82
	v_lshl_add_u64 v[80:81], v[62:63], 0, s[2:3]
	v_cvt_pk_bf16_f32 v82, v83, s0
	v_lshl_add_u64 v[80:81], v[80:81], 0, v[188:189]
	global_store_short v[80:81], v82, off
	v_cvt_pk_bf16_f32 v82, v84, s0
	global_store_short v[80:81], v82, off offset:128
	v_cvt_pk_bf16_f32 v82, v85, s0
	global_store_short v[80:81], v82, off offset:256
	s_waitcnt vmcnt(23)
	v_lshlrev_b32_e32 v82, 16, v115
	s_waitcnt vmcnt(22)
	v_lshlrev_b32_e32 v83, 16, v117
	v_pk_mul_f32 v[84:85], v[82:83], v[82:83]
	s_waitcnt vmcnt(20)
	v_lshlrev_b32_e32 v88, 16, v119
	s_waitcnt vmcnt(19)
	v_lshlrev_b32_e32 v91, 16, v94
	s_waitcnt vmcnt(18)
	v_lshlrev_b32_e32 v90, 16, v95
	v_pk_mul_f32 v[92:93], v[90:91], v[90:91]
	v_lshlrev_b32_e32 v89, 16, v118
	v_mov_b32_e32 v94, v93
	v_mov_b32_e32 v95, v85
	v_pk_fma_f32 v[94:95], v[88:89], v[88:89], v[94:95]
	v_mov_b32_e32 v93, v84
	v_pk_add_f32 v[84:85], v[92:93], v[94:95]
	ds_bpermute_b32 v93, v102, v85
	ds_bpermute_b32 v92, v102, v84
	s_waitcnt lgkmcnt(0)
	v_pk_add_f32 v[84:85], v[84:85], v[92:93]
	ds_bpermute_b32 v93, v103, v85
	ds_bpermute_b32 v92, v103, v84
	s_waitcnt lgkmcnt(0)
	v_pk_add_f32 v[84:85], v[84:85], v[92:93]
	s_waitcnt lgkmcnt(0)
	s_nop 1
	v_add_f32_dpp v84, v84, v84 row_mirror row_mask:0xf bank_mask:0xf
	v_add_f32_dpp v85, v85, v85 row_mirror row_mask:0xf bank_mask:0xf
	s_waitcnt lgkmcnt(0)
	s_nop 1
	v_add_f32_dpp v84, v84, v84 row_half_mirror row_mask:0xf bank_mask:0xf
	v_add_f32_dpp v85, v85, v85 row_half_mirror row_mask:0xf bank_mask:0xf
	s_waitcnt lgkmcnt(0)
	s_nop 1
	v_add_f32_dpp v84, v84, v84 quad_perm:[2,3,0,1] row_mask:0xf bank_mask:0xf
	v_add_f32_dpp v85, v85, v85 quad_perm:[2,3,0,1] row_mask:0xf bank_mask:0xf
	s_waitcnt lgkmcnt(0)
	s_nop 1
	v_add_f32_dpp v84, v84, v84 quad_perm:[1,0,3,2] row_mask:0xf bank_mask:0xf
	v_add_f32_dpp v85, v85, v85 quad_perm:[1,0,3,2] row_mask:0xf bank_mask:0xf
	s_nop 0
	v_pk_fma_f32 v[84:85], v[84:85], s[0:1], v[66:67] op_sel_hi:[1,0,0]
	s_waitcnt vmcnt(13)
	v_lshlrev_b32_e32 v93, 16, v124
	v_mul_f32_e32 v92, 0x4b800000, v85
	v_cmp_gt_f32_e64 s[38:39], s33, v85
	v_cmp_gt_f32_e64 s[36:37], s33, v84
	s_nop 0
	v_cndmask_b32_e64 v85, v85, v92, s[38:39]
	v_rsq_f32_e32 v85, v85
	s_nop 0
	v_mul_f32_e32 v92, 0x45800000, v85
	v_cndmask_b32_e64 v85, v85, v92, s[38:39]
	v_mul_f32_e32 v92, v96, v85
	v_mul_f32_e32 v83, v92, v83
	v_mul_f32_e32 v92, v97, v85
	v_mul_f32_e32 v85, v98, v85
	v_mul_f32_e32 v82, v85, v82
	ds_bpermute_b32 v85, v102, v82
	v_mul_f32_e32 v89, v92, v89
	s_waitcnt vmcnt(12)
	v_lshlrev_b32_e32 v92, 16, v125
	v_pk_mul_f32 v[94:95], v[92:93], v[92:93]
	v_lshl_add_u64 v[124:125], s[26:27], 0, v[28:29]
	s_waitcnt lgkmcnt(0)
	v_mul_f32_e32 v85, v79, v85
	v_cndmask_b32_e64 v85, v85, -v85, vcc
	v_fmac_f32_e32 v85, v78, v82
	v_mul_f32_e32 v82, 0x3dd53b94, v83
	v_cvt_pk_bf16_f32 v82, v82, s0
	global_store_short v[76:77], v82, off offset:1536
	v_mul_f32_e32 v82, 0x3dd53b94, v89
	v_cvt_pk_bf16_f32 v82, v82, s0
	global_store_short v[76:77], v82, off offset:1664
	v_mul_f32_e32 v82, 0x3dd53b94, v85
	v_cvt_pk_bf16_f32 v82, v82, s0
	global_store_short v[76:77], v82, off offset:1792
	v_mul_f32_e32 v82, 0x4b800000, v84
	v_cndmask_b32_e64 v82, v84, v82, s[36:37]
	v_rsq_f32_e32 v82, v82
	v_mov_b32_e32 v114, v95
	v_mul_f32_e32 v83, 0x45800000, v82
	v_cndmask_b32_e64 v82, v82, v83, s[36:37]
	v_mul_f32_e32 v83, v99, v82
	v_mul_f32_e32 v84, v100, v82
	v_mul_f32_e32 v82, v101, v82
	v_mul_f32_e32 v82, v82, v90
	ds_bpermute_b32 v85, v102, v82
	v_mul_f32_e32 v83, v83, v91
	v_mul_f32_e32 v84, v84, v88
	v_lshlrev_b32_e32 v90, 16, v123
	v_lshlrev_b32_e32 v91, 16, v122
	s_waitcnt lgkmcnt(0)
	v_mul_f32_e32 v79, v79, v85
	v_cndmask_b32_e64 v85, v79, -v79, vcc
	v_fmac_f32_e32 v85, v78, v82
	v_cvt_pk_bf16_f32 v82, v83, s0
	global_store_short v[80:81], v82, off offset:1536
	v_cvt_pk_bf16_f32 v82, v84, s0
	global_store_short v[80:81], v82, off offset:1664
	v_cvt_pk_bf16_f32 v82, v85, s0
	global_store_short v[80:81], v82, off offset:1792
	v_lshlrev_b32_e32 v83, 16, v121
	v_lshlrev_b32_e32 v82, 16, v120
	v_pk_mul_f32 v[84:85], v[82:83], v[82:83]
	v_lshl_add_u64 v[88:89], v[76:77], 0, s[68:69]
	v_mov_b32_e32 v115, v85
	v_pk_fma_f32 v[114:115], v[90:91], v[90:91], v[114:115]
	v_mov_b32_e32 v95, v84
	v_pk_add_f32 v[84:85], v[94:95], v[114:115]
	ds_bpermute_b32 v95, v102, v85
	ds_bpermute_b32 v94, v102, v84
	v_lshl_add_u64 v[78:79], v[80:81], 0, s[70:71]
	s_waitcnt lgkmcnt(0)
	v_pk_add_f32 v[84:85], v[84:85], v[94:95]
	ds_bpermute_b32 v95, v103, v85
	ds_bpermute_b32 v94, v103, v84
	s_waitcnt lgkmcnt(0)
	v_pk_add_f32 v[84:85], v[84:85], v[94:95]
	s_waitcnt lgkmcnt(0)
	s_nop 1
	v_add_f32_dpp v84, v84, v84 row_mirror row_mask:0xf bank_mask:0xf
	v_add_f32_dpp v85, v85, v85 row_mirror row_mask:0xf bank_mask:0xf
	s_waitcnt lgkmcnt(0)
	s_nop 1
	v_add_f32_dpp v84, v84, v84 row_half_mirror row_mask:0xf bank_mask:0xf
	v_add_f32_dpp v85, v85, v85 row_half_mirror row_mask:0xf bank_mask:0xf
	s_waitcnt lgkmcnt(0)
	s_nop 1
	v_add_f32_dpp v84, v84, v84 quad_perm:[2,3,0,1] row_mask:0xf bank_mask:0xf
	v_add_f32_dpp v85, v85, v85 quad_perm:[2,3,0,1] row_mask:0xf bank_mask:0xf
	s_waitcnt lgkmcnt(0)
	s_nop 1
	v_add_f32_dpp v84, v84, v84 quad_perm:[1,0,3,2] row_mask:0xf bank_mask:0xf
	v_add_f32_dpp v85, v85, v85 quad_perm:[1,0,3,2] row_mask:0xf bank_mask:0xf
	s_nop 0
	v_pk_fma_f32 v[84:85], v[84:85], s[0:1], v[66:67] op_sel_hi:[1,0,0]
	s_nop 0
	v_mul_f32_e32 v94, 0x4b800000, v85
	v_cmp_gt_f32_e64 s[38:39], s33, v85
	v_cmp_gt_f32_e64 s[36:37], s33, v84
	s_nop 0
	v_cndmask_b32_e64 v85, v85, v94, s[38:39]
	v_rsq_f32_e32 v85, v85
	s_nop 0
	v_mul_f32_e32 v94, 0x45800000, v85
	v_cndmask_b32_e64 v85, v85, v94, s[38:39]
	v_mul_f32_e32 v94, v96, v85
	v_mul_f32_e32 v83, v94, v83
	v_mul_f32_e32 v94, v97, v85
	v_mul_f32_e32 v85, v98, v85
	v_mul_f32_e32 v82, v85, v82
	ds_bpermute_b32 v85, v102, v82
	v_mul_f32_e32 v91, v94, v91
	s_waitcnt lgkmcnt(0)
; DI u16 f2bf(float a) { return (u16)(pack2(a, 0.f) & 0xffffu); }
; DI float bf2f(u16 v) { return __uint_as_float(((unsigned)v) << 16); }
; DI float wave_sum(float v) {
; #pragma unroll
;   for (int o = 32; o; o >>= 1) v += __shfl_xor(v, o);
;   return v;
; DI void prep_item(const Params& p, int l, int item) {
;     ...
;       for (int j = 0; j < 4; j++) {
;         const size_t t = tb + t4 + j;
;         csa[j] = rope[(s0 + t4 + j) * 32 + (lane & 31)];
;         const u16* qr = qb + t * 768 + hd * 192;
;         qa[j][0] = qr[lane]; qa[j][1] = qr[64 + lane]; qa[j][2] = qr[128 + lane];
;         const u16* kvr = kvraw + t * 1024 + hd * 256;
;         ka[j][0] = kvr[lane]; ka[j][1] = kvr[64 + lane]; ka[j][2] = z[t * 1760 + 896 + lane];
;         vv[t4 + j] = *(const unsigned*)(kvr + 128 + 2 * lane);
;       }
; #pragma unroll
;       for (int j = 0; j < 4; j++) {
;         const size_t t = tb + t4 + j;
;         const float2 cs = csa[j];
;         u16* qr = qb + t * 768 + hd * 192;
;         float q0 = bf2f(qa[j][0]), q1 = bf2f(qa[j][1]), q2 = bf2f(qa[j][2]);
;         float ss = wave_sum(q0 * q0 + q1 * q1 + q2 * q2);
;         float rs = rsqrtf(ss * (1.f / 192.f) + EPS);
;         q0 *= rs * gq0; q1 *= rs * gq1; q2 *= rs * gq2;
;         float pr = __shfl_xor(q2, 32);
;         float rot = (lane < 32) ? (q2 * cs.x - pr * cs.y) : (q2 * cs.x + pr * cs.y);
;         qr[lane] = f2bf(q0 * QS); qr[64 + lane] = f2bf(q1 * QS); qr[128 + lane] = f2bf(rot * QS);
;         float k0 = bf2f(ka[j][0]), k1 = bf2f(ka[j][1]), k2 = bf2f(ka[j][2]);
;         float ks = wave_sum(k0 * k0 + k1 * k1 + k2 * k2);
;         float rk = rsqrtf(ks * (1.f / 192.f) + EPS);
;         k0 *= rk * gk0; k1 *= rk * gk1; k2 *= rk * gk2;
;         float pk = __shfl_xor(k2, 32);
;         float rotk = (lane < 32) ? (k2 * cs.x - pk * cs.y) : (k2 * cs.x + pk * cs.y);
;         u16* kr = kb + t * 768 + hd * 192;
;         kr[lane] = f2bf(k0); kr[64 + lane] = f2bf(k1); kr[128 + lane] = f2bf(rotk);
;       }
	v_mul_f32_e32 v85, v75, v85
	v_cndmask_b32_e64 v85, v85, -v85, vcc
	v_fmac_f32_e32 v85, v74, v82
	v_mul_f32_e32 v82, 0x3dd53b94, v83
	v_cvt_pk_bf16_f32 v82, v82, s0
	global_store_short v[76:77], v82, off offset:3072
	v_mul_f32_e32 v82, 0x3dd53b94, v91
	v_cvt_pk_bf16_f32 v82, v82, s0
	global_store_short v[76:77], v82, off offset:3200
	v_mul_f32_e32 v82, 0x3dd53b94, v85
	v_cvt_pk_bf16_f32 v82, v82, s0
	global_store_short v[76:77], v82, off offset:3328
	v_mul_f32_e32 v76, 0x4b800000, v84
	v_cndmask_b32_e64 v76, v84, v76, s[36:37]
	v_rsq_f32_e32 v76, v76
	v_lshl_add_u64 v[84:85], v[80:81], 0, s[68:69]
	v_mul_f32_e32 v77, 0x45800000, v76
	v_cndmask_b32_e64 v76, v76, v77, s[36:37]
	v_mul_f32_e32 v77, v99, v76
	v_mul_f32_e32 v82, v100, v76
	v_mul_f32_e32 v76, v101, v76
	v_mul_f32_e32 v76, v76, v92
	ds_bpermute_b32 v83, v102, v76
	v_mul_f32_e32 v77, v77, v93
	v_mul_f32_e32 v82, v82, v90
	v_lshl_add_u64 v[90:91], v[86:87], 0, s[68:69]
	v_lshl_add_u64 v[118:119], v[90:91], 0, s[68:69]
	s_waitcnt lgkmcnt(0)
	v_mul_f32_e32 v75, v75, v83
	v_cndmask_b32_e64 v75, v75, -v75, vcc
	v_fmac_f32_e32 v75, v74, v76
	v_cvt_pk_bf16_f32 v74, v77, s0
	global_store_short v[80:81], v74, off offset:3072
	v_cvt_pk_bf16_f32 v74, v82, s0
	global_store_short v[80:81], v74, off offset:3200
	v_cvt_pk_bf16_f32 v74, v75, s0
	global_store_short v[80:81], v74, off offset:3328
	s_waitcnt vmcnt(22)
	v_lshlrev_b32_e32 v75, 16, v127
	v_lshlrev_b32_e32 v74, 16, v126
	s_waitcnt vmcnt(19)
	v_lshlrev_b32_e32 v83, 16, v130
	s_waitcnt vmcnt(18)
	v_lshlrev_b32_e32 v82, 16, v131
	v_pk_mul_f32 v[76:77], v[74:75], v[74:75]
	v_pk_mul_f32 v[92:93], v[82:83], v[82:83]
	v_lshlrev_b32_e32 v80, 16, v129
	v_lshlrev_b32_e32 v81, 16, v128
	v_mov_b32_e32 v94, v93
	v_mov_b32_e32 v95, v77
	v_pk_fma_f32 v[94:95], v[80:81], v[80:81], v[94:95]
	v_mov_b32_e32 v93, v76
	v_pk_add_f32 v[76:77], v[92:93], v[94:95]
	ds_bpermute_b32 v93, v102, v77
	ds_bpermute_b32 v92, v102, v76
	v_lshl_add_u64 v[126:127], v[124:125], 0, v[188:189]
	v_lshl_add_u64 v[124:125], v[124:125], 0, v[64:65]
	v_lshl_add_u64 v[94:95], v[88:89], 0, s[68:69]
	v_lshl_add_u64 v[130:131], v[70:71], 0, s[68:69]
	s_waitcnt lgkmcnt(0)
	v_pk_add_f32 v[76:77], v[76:77], v[92:93]
	ds_bpermute_b32 v93, v103, v77
	ds_bpermute_b32 v92, v103, v76
	s_waitcnt lgkmcnt(0)
	v_pk_add_f32 v[76:77], v[76:77], v[92:93]
	s_waitcnt lgkmcnt(0)
	s_nop 1
	v_add_f32_dpp v76, v76, v76 row_mirror row_mask:0xf bank_mask:0xf
	v_add_f32_dpp v77, v77, v77 row_mirror row_mask:0xf bank_mask:0xf
	s_waitcnt lgkmcnt(0)
	s_nop 1
	v_add_f32_dpp v76, v76, v76 row_half_mirror row_mask:0xf bank_mask:0xf
	v_add_f32_dpp v77, v77, v77 row_half_mirror row_mask:0xf bank_mask:0xf
	s_waitcnt lgkmcnt(0)
	s_nop 1
	v_add_f32_dpp v76, v76, v76 quad_perm:[2,3,0,1] row_mask:0xf bank_mask:0xf
	v_add_f32_dpp v77, v77, v77 quad_perm:[2,3,0,1] row_mask:0xf bank_mask:0xf
	s_waitcnt lgkmcnt(0)
	s_nop 1
	v_add_f32_dpp v76, v76, v76 quad_perm:[1,0,3,2] row_mask:0xf bank_mask:0xf
	v_add_f32_dpp v77, v77, v77 quad_perm:[1,0,3,2] row_mask:0xf bank_mask:0xf
	s_nop 0
	v_pk_fma_f32 v[76:77], v[76:77], s[0:1], v[66:67] op_sel_hi:[1,0,0]
	s_nop 0
	v_mul_f32_e32 v92, 0x4b800000, v77
	v_cmp_gt_f32_e64 s[38:39], s33, v77
	v_cmp_gt_f32_e64 s[36:37], s33, v76
	s_nop 0
	v_cndmask_b32_e64 v77, v77, v92, s[38:39]
	v_rsq_f32_e32 v77, v77
	s_nop 0
	v_mul_f32_e32 v92, 0x45800000, v77
	v_cndmask_b32_e64 v77, v77, v92, s[38:39]
	v_mul_f32_e32 v92, v96, v77
	v_mul_f32_e32 v75, v92, v75
	v_mul_f32_e32 v92, v97, v77
	v_mul_f32_e32 v77, v98, v77
	v_mul_f32_e32 v74, v77, v74
	ds_bpermute_b32 v77, v102, v74
	v_mul_f32_e32 v81, v92, v81
	s_waitcnt lgkmcnt(0)
	v_mul_f32_e32 v77, v73, v77
	v_cndmask_b32_e64 v77, v77, -v77, vcc
	v_fmac_f32_e32 v77, v72, v74
	v_mul_f32_e32 v74, 0x3dd53b94, v75
	v_cvt_pk_bf16_f32 v74, v74, s0
	global_store_short v[86:87], v74, off offset:3072
	v_mul_f32_e32 v74, 0x3dd53b94, v81
	v_cvt_pk_bf16_f32 v74, v74, s0
	global_store_short v[86:87], v74, off offset:3200
	v_mul_f32_e32 v74, 0x3dd53b94, v77
	v_cvt_pk_bf16_f32 v74, v74, s0
	global_store_short v[86:87], v74, off offset:3328
	v_mul_f32_e32 v74, 0x4b800000, v76
	v_cndmask_b32_e64 v74, v76, v74, s[36:37]
	v_rsq_f32_e32 v74, v74
	v_lshl_add_u64 v[86:87], v[78:79], 0, s[68:69]
	v_mul_f32_e32 v75, 0x45800000, v74
	v_cndmask_b32_e64 v74, v74, v75, s[36:37]
	v_mul_f32_e32 v75, v99, v74
	v_mul_f32_e32 v76, v100, v74
	v_mul_f32_e32 v74, v101, v74
	v_mul_f32_e32 v74, v74, v82
	ds_bpermute_b32 v77, v102, v74
	v_mul_f32_e32 v75, v75, v83
	v_mul_f32_e32 v76, v76, v80
	s_waitcnt lgkmcnt(0)
	v_mul_f32_e32 v73, v73, v77
	v_cndmask_b32_e64 v73, v73, -v73, vcc
	v_fmac_f32_e32 v73, v72, v74
	v_cvt_pk_bf16_f32 v72, v75, s0
	global_store_short v[78:79], v72, off offset:3072
	v_cvt_pk_bf16_f32 v72, v76, s0
	global_store_short v[78:79], v72, off offset:3200
	v_cvt_pk_bf16_f32 v72, v73, s0
	global_store_short v[78:79], v72, off offset:3328
	v_lshl_add_u64 v[72:73], s[26:27], 0, v[18:19]
	v_lshl_add_u64 v[114:115], v[72:73], 0, v[188:189]
	v_lshl_add_u64 v[72:73], v[72:73], 0, v[64:65]
	global_load_dwordx2 v[92:93], v[0:1], off offset:1024
	global_load_dword v80, v[72:73], off offset:256
	global_load_dwordx2 v[116:117], v[0:1], off offset:1280
	v_lshl_add_u64 v[72:73], s[26:27], 0, v[22:23]
	v_lshl_add_u64 v[120:121], v[72:73], 0, v[188:189]
	v_lshl_add_u64 v[72:73], v[72:73], 0, v[64:65]
	global_load_dword v81, v[72:73], off offset:256
	global_load_dwordx2 v[78:79], v[0:1], off offset:1536
	v_lshl_add_u64 v[72:73], s[26:27], 0, v[24:25]
	v_lshl_add_u64 v[122:123], v[72:73], 0, v[188:189]
	v_lshl_add_u64 v[72:73], v[72:73], 0, v[64:65]
	global_load_dword v82, v[72:73], off offset:256
	global_load_dwordx2 v[76:77], v[0:1], off offset:1792
	global_load_dword v83, v[124:125], off offset:256
	global_load_ushort v113, v[88:89], off offset:3328
	s_nop 0
	global_load_ushort v124, v[88:89], off offset:3072
	v_lshl_add_u64 v[74:75], v[94:95], 0, s[68:69]
	v_lshl_add_u64 v[72:73], v[118:119], 0, s[68:69]
	s_waitcnt vmcnt(0)
; DI u16 f2bf(float a) { return (u16)(pack2(a, 0.f) & 0xffffu); }
; DI float bf2f(u16 v) { return __uint_as_float(((unsigned)v) << 16); }
; DI float wave_sum(float v) {
; #pragma unroll
;   for (int o = 32; o; o >>= 1) v += __shfl_xor(v, o);
;   return v;
; DI void prep_item(const Params& p, int l, int item) {
;     ...
;       for (int j = 0; j < 4; j++) {
;         const size_t t = tb + t4 + j;
;         csa[j] = rope[(s0 + t4 + j) * 32 + (lane & 31)];
;         const u16* qr = qb + t * 768 + hd * 192;
;         qa[j][0] = qr[lane]; qa[j][1] = qr[64 + lane]; qa[j][2] = qr[128 + lane];
;         const u16* kvr = kvraw + t * 1024 + hd * 256;
;         ka[j][0] = kvr[lane]; ka[j][1] = kvr[64 + lane]; ka[j][2] = z[t * 1760 + 896 + lane];
;         vv[t4 + j] = *(const unsigned*)(kvr + 128 + 2 * lane);
;       }
; #pragma unroll
;       for (int j = 0; j < 4; j++) {
;         const size_t t = tb + t4 + j;
;         const float2 cs = csa[j];
;         u16* qr = qb + t * 768 + hd * 192;
;         float q0 = bf2f(qa[j][0]), q1 = bf2f(qa[j][1]), q2 = bf2f(qa[j][2]);
;         float ss = wave_sum(q0 * q0 + q1 * q1 + q2 * q2);
;         float rs = rsqrtf(ss * (1.f / 192.f) + EPS);
;         q0 *= rs * gq0; q1 *= rs * gq1; q2 *= rs * gq2;
;         float pr = __shfl_xor(q2, 32);
;         float rot = (lane < 32) ? (q2 * cs.x - pr * cs.y) : (q2 * cs.x + pr * cs.y);
;         qr[lane] = f2bf(q0 * QS); qr[64 + lane] = f2bf(q1 * QS); qr[128 + lane] = f2bf(rot * QS);
;         float k0 = bf2f(ka[j][0]), k1 = bf2f(ka[j][1]), k2 = bf2f(ka[j][2]);
;         float ks = wave_sum(k0 * k0 + k1 * k1 + k2 * k2);
;         float rk = rsqrtf(ks * (1.f / 192.f) + EPS);
;         k0 *= rk * gk0; k1 *= rk * gk1; k2 *= rk * gk2;
;         float pk = __shfl_xor(k2, 32);
;         float rotk = (lane < 32) ? (k2 * cs.x - pk * cs.y) : (k2 * cs.x + pk * cs.y);
;         u16* kr = kb + t * 768 + hd * 192;
;         kr[lane] = f2bf(k0); kr[64 + lane] = f2bf(k1); kr[128 + lane] = f2bf(rotk);
;       }
	v_lshlrev_b32_e32 v125, 16, v124
	v_lshlrev_b32_e32 v124, 16, v113
	global_load_ushort v113, v[114:115], off offset:128
	s_nop 0
	global_load_ushort v88, v[88:89], off offset:3200
	v_pk_mul_f32 v[128:129], v[124:125], v[124:125]
	s_waitcnt vmcnt(0)
	v_lshlrev_b32_e32 v89, 16, v88
	v_lshlrev_b32_e32 v88, 16, v113
	global_load_ushort v113, v[114:115], off
	s_nop 0
	global_load_ushort v114, v[20:21], off
	v_mov_b32_e32 v135, v129
	s_waitcnt vmcnt(1)
	v_lshlrev_b32_e32 v115, 16, v113
	s_waitcnt vmcnt(0)
	v_lshlrev_b32_e32 v114, 16, v114
	v_pk_mul_f32 v[132:133], v[114:115], v[114:115]
	s_nop 0
	v_mov_b32_e32 v134, v133
	v_pk_fma_f32 v[134:135], v[88:89], v[88:89], v[134:135]
	v_mov_b32_e32 v133, v128
	v_pk_add_f32 v[128:129], v[132:133], v[134:135]
	ds_bpermute_b32 v133, v102, v129
	ds_bpermute_b32 v132, v102, v128
	s_waitcnt lgkmcnt(0)
	v_pk_add_f32 v[128:129], v[128:129], v[132:133]
	ds_bpermute_b32 v133, v103, v129
	ds_bpermute_b32 v132, v103, v128
	s_waitcnt lgkmcnt(0)
	v_pk_add_f32 v[128:129], v[128:129], v[132:133]
	s_waitcnt lgkmcnt(0)
	s_nop 1
	v_add_f32_dpp v128, v128, v128 row_mirror row_mask:0xf bank_mask:0xf
	v_add_f32_dpp v129, v129, v129 row_mirror row_mask:0xf bank_mask:0xf
	s_waitcnt lgkmcnt(0)
	s_nop 1
	v_add_f32_dpp v128, v128, v128 row_half_mirror row_mask:0xf bank_mask:0xf
	v_add_f32_dpp v129, v129, v129 row_half_mirror row_mask:0xf bank_mask:0xf
	s_waitcnt lgkmcnt(0)
	s_nop 1
	v_add_f32_dpp v128, v128, v128 quad_perm:[2,3,0,1] row_mask:0xf bank_mask:0xf
	v_add_f32_dpp v129, v129, v129 quad_perm:[2,3,0,1] row_mask:0xf bank_mask:0xf
	s_waitcnt lgkmcnt(0)
	s_nop 1
	v_add_f32_dpp v128, v128, v128 quad_perm:[1,0,3,2] row_mask:0xf bank_mask:0xf
	v_add_f32_dpp v129, v129, v129 quad_perm:[1,0,3,2] row_mask:0xf bank_mask:0xf
	s_nop 0
	v_pk_fma_f32 v[128:129], v[128:129], s[0:1], v[66:67] op_sel_hi:[1,0,0]
	s_nop 0
	v_mul_f32_e32 v113, 0x4b800000, v129
	v_cmp_gt_f32_e64 s[38:39], s33, v129
	v_cmp_gt_f32_e64 s[36:37], s33, v128
	s_nop 0
	v_cndmask_b32_e64 v113, v129, v113, s[38:39]
	v_rsq_f32_e32 v113, v113
	s_nop 0
	v_mul_f32_e32 v129, 0x45800000, v113
	v_cndmask_b32_e64 v113, v113, v129, s[38:39]
	v_mul_f32_e32 v129, v96, v113
	v_mul_f32_e32 v125, v129, v125
	v_mul_f32_e32 v129, v97, v113
	v_mul_f32_e32 v113, v98, v113
	v_mul_f32_e32 v113, v113, v124
	ds_bpermute_b32 v124, v102, v113
	v_mul_f32_e32 v89, v129, v89
	v_mul_f32_e32 v89, 0x3dd53b94, v89
	v_cvt_pk_bf16_f32 v89, v89, s0
	s_waitcnt lgkmcnt(0)
	v_mul_f32_e32 v124, v93, v124
	v_cndmask_b32_e64 v124, v124, -v124, vcc
	v_fmac_f32_e32 v124, v92, v113
	v_mul_f32_e32 v113, 0x3dd53b94, v125
	global_load_ushort v125, v[90:91], off offset:3328
	global_load_ushort v129, v[90:91], off offset:3072
	global_load_ushort v132, v[120:121], off offset:128
	global_load_ushort v133, v[90:91], off offset:3200
	s_nop 0
	global_load_ushort v120, v[120:121], off
	s_nop 0
	global_load_ushort v121, v[20:21], off offset:3520
	global_load_ushort v134, v[94:95], off offset:3328
	global_load_ushort v135, v[94:95], off offset:3072
	global_load_ushort v136, v[122:123], off offset:128
	global_load_ushort v137, v[94:95], off offset:3200
	s_nop 0
	global_load_ushort v122, v[122:123], off
	s_nop 0
	global_load_ushort v123, v[26:27], off
	global_load_ushort v138, v[118:119], off offset:3328
	global_load_ushort v139, v[118:119], off offset:3072
	global_load_ushort v140, v[126:127], off offset:128
	global_load_ushort v141, v[118:119], off offset:3200
	s_nop 0
	global_load_ushort v126, v[126:127], off
	s_nop 0
	global_load_ushort v127, v[26:27], off offset:3520
	v_cvt_pk_bf16_f32 v113, v113, s0
	global_store_short v[70:71], v89, off offset:3200
	v_mul_f32_e32 v89, 0x3dd53b94, v124
	v_cvt_pk_bf16_f32 v89, v89, s0
	global_store_short v[70:71], v113, off offset:3072
	global_store_short v[70:71], v89, off offset:3328
	v_mul_f32_e32 v70, 0x4b800000, v128
	v_cndmask_b32_e64 v70, v128, v70, s[36:37]
	v_rsq_f32_e32 v70, v70
	s_waitcnt vmcnt(16)
	v_lshlrev_b32_e32 v95, 16, v120
	v_mul_f32_e32 v71, 0x45800000, v70
	v_cndmask_b32_e64 v70, v70, v71, s[36:37]
	v_mul_f32_e32 v71, v99, v70
	v_mul_f32_e32 v89, v100, v70
	v_mul_f32_e32 v70, v101, v70
	v_mul_f32_e32 v70, v70, v114
	v_mul_f32_e32 v88, v89, v88
	ds_bpermute_b32 v89, v102, v70
	v_mul_f32_e32 v71, v71, v115
	v_cvt_pk_bf16_f32 v88, v88, s0
	v_cvt_pk_bf16_f32 v90, v71, s0
	global_store_short v[84:85], v88, off offset:3200
	s_waitcnt lgkmcnt(0)
	v_mul_f32_e32 v89, v93, v89
	v_cndmask_b32_e64 v89, v89, -v89, vcc
	v_fmac_f32_e32 v89, v92, v70
	v_cvt_pk_bf16_f32 v88, v89, s0
	v_lshl_add_u64 v[70:71], v[84:85], 0, s[68:69]
	global_store_short v[84:85], v90, off offset:3072
	global_store_short v[84:85], v88, off offset:3328
	v_lshlrev_b32_e32 v85, 16, v129
	v_lshlrev_b32_e32 v84, 16, v125
	s_waitcnt vmcnt(18)
	v_lshlrev_b32_e32 v94, 16, v121
	v_pk_mul_f32 v[88:89], v[84:85], v[84:85]
	v_pk_mul_f32 v[114:115], v[94:95], v[94:95]
	v_lshlrev_b32_e32 v93, 16, v133
	v_lshlrev_b32_e32 v92, 16, v132
	v_mov_b32_e32 v118, v115
	v_mov_b32_e32 v119, v89
	v_pk_fma_f32 v[118:119], v[92:93], v[92:93], v[118:119]
	v_mov_b32_e32 v115, v88
	v_pk_add_f32 v[88:89], v[114:115], v[118:119]
	ds_bpermute_b32 v115, v102, v89
	ds_bpermute_b32 v114, v102, v88
	v_lshl_add_u64 v[90:91], v[68:69], 0, s[68:69]
	v_lshl_add_u64 v[128:129], s[26:27], 0, v[40:41]
	s_waitcnt lgkmcnt(0)
	v_pk_add_f32 v[88:89], v[88:89], v[114:115]
	ds_bpermute_b32 v115, v103, v89
	ds_bpermute_b32 v114, v103, v88
	s_waitcnt lgkmcnt(0)
	v_pk_add_f32 v[88:89], v[88:89], v[114:115]
	s_waitcnt lgkmcnt(0)
	s_nop 1
	v_add_f32_dpp v88, v88, v88 row_mirror row_mask:0xf bank_mask:0xf
	v_add_f32_dpp v89, v89, v89 row_mirror row_mask:0xf bank_mask:0xf
	s_waitcnt lgkmcnt(0)
; DI u16 f2bf(float a) { return (u16)(pack2(a, 0.f) & 0xffffu); }
; DI float bf2f(u16 v) { return __uint_as_float(((unsigned)v) << 16); }
; DI float wave_sum(float v) {
; #pragma unroll
;   for (int o = 32; o; o >>= 1) v += __shfl_xor(v, o);
;   return v;
; DI void prep_item(const Params& p, int l, int item) {
;     ...
;       for (int j = 0; j < 4; j++) {
;         const size_t t = tb + t4 + j;
;         csa[j] = rope[(s0 + t4 + j) * 32 + (lane & 31)];
;         const u16* qr = qb + t * 768 + hd * 192;
;         qa[j][0] = qr[lane]; qa[j][1] = qr[64 + lane]; qa[j][2] = qr[128 + lane];
;         const u16* kvr = kvraw + t * 1024 + hd * 256;
;         ka[j][0] = kvr[lane]; ka[j][1] = kvr[64 + lane]; ka[j][2] = z[t * 1760 + 896 + lane];
;         vv[t4 + j] = *(const unsigned*)(kvr + 128 + 2 * lane);
;       }
; #pragma unroll
;       for (int j = 0; j < 4; j++) {
;         const size_t t = tb + t4 + j;
;         const float2 cs = csa[j];
;         u16* qr = qb + t * 768 + hd * 192;
;         float q0 = bf2f(qa[j][0]), q1 = bf2f(qa[j][1]), q2 = bf2f(qa[j][2]);
;         float ss = wave_sum(q0 * q0 + q1 * q1 + q2 * q2);
;         float rs = rsqrtf(ss * (1.f / 192.f) + EPS);
;         q0 *= rs * gq0; q1 *= rs * gq1; q2 *= rs * gq2;
;         float pr = __shfl_xor(q2, 32);
;         float rot = (lane < 32) ? (q2 * cs.x - pr * cs.y) : (q2 * cs.x + pr * cs.y);
;         qr[lane] = f2bf(q0 * QS); qr[64 + lane] = f2bf(q1 * QS); qr[128 + lane] = f2bf(rot * QS);
;         float k0 = bf2f(ka[j][0]), k1 = bf2f(ka[j][1]), k2 = bf2f(ka[j][2]);
;         float ks = wave_sum(k0 * k0 + k1 * k1 + k2 * k2);
;         float rk = rsqrtf(ks * (1.f / 192.f) + EPS);
;         k0 *= rk * gk0; k1 *= rk * gk1; k2 *= rk * gk2;
;         float pk = __shfl_xor(k2, 32);
;         float rotk = (lane < 32) ? (k2 * cs.x - pk * cs.y) : (k2 * cs.x + pk * cs.y);
;         u16* kr = kb + t * 768 + hd * 192;
;         kr[lane] = f2bf(k0); kr[64 + lane] = f2bf(k1); kr[128 + lane] = f2bf(rotk);
;       }
	s_nop 1
	v_add_f32_dpp v88, v88, v88 row_half_mirror row_mask:0xf bank_mask:0xf
	v_add_f32_dpp v89, v89, v89 row_half_mirror row_mask:0xf bank_mask:0xf
	s_waitcnt lgkmcnt(0)
	s_nop 1
	v_add_f32_dpp v88, v88, v88 quad_perm:[2,3,0,1] row_mask:0xf bank_mask:0xf
	v_add_f32_dpp v89, v89, v89 quad_perm:[2,3,0,1] row_mask:0xf bank_mask:0xf
	s_waitcnt lgkmcnt(0)
	s_nop 1
	v_add_f32_dpp v88, v88, v88 quad_perm:[1,0,3,2] row_mask:0xf bank_mask:0xf
	v_add_f32_dpp v89, v89, v89 quad_perm:[1,0,3,2] row_mask:0xf bank_mask:0xf
	s_nop 0
	v_pk_fma_f32 v[88:89], v[88:89], s[0:1], v[66:67] op_sel_hi:[1,0,0]
	s_nop 0
	v_mul_f32_e32 v113, 0x4b800000, v89
	v_cmp_gt_f32_e64 s[38:39], s33, v89
	v_cmp_gt_f32_e64 s[36:37], s33, v88
	s_nop 0
	v_cndmask_b32_e64 v89, v89, v113, s[38:39]
	v_rsq_f32_e32 v89, v89
	s_nop 0
	v_mul_f32_e32 v113, 0x45800000, v89
	v_cndmask_b32_e64 v89, v89, v113, s[38:39]
	v_mul_f32_e32 v113, v96, v89
	v_mul_f32_e32 v85, v113, v85
	v_mul_f32_e32 v113, v97, v89
	v_mul_f32_e32 v89, v98, v89
	v_mul_f32_e32 v84, v89, v84
	ds_bpermute_b32 v89, v102, v84
	v_mul_f32_e32 v93, v113, v93
	s_waitcnt lgkmcnt(0)
	v_mul_f32_e32 v89, v117, v89
	v_cndmask_b32_e64 v89, v89, -v89, vcc
	v_fmac_f32_e32 v89, v116, v84
	v_mul_f32_e32 v84, 0x3dd53b94, v85
	v_cvt_pk_bf16_f32 v84, v84, s0
	global_store_short v[68:69], v84, off offset:3072
	v_mul_f32_e32 v84, 0x3dd53b94, v93
	v_cvt_pk_bf16_f32 v84, v84, s0
	global_store_short v[68:69], v84, off offset:3200
	v_mul_f32_e32 v84, 0x3dd53b94, v89
	v_cvt_pk_bf16_f32 v84, v84, s0
	global_store_short v[68:69], v84, off offset:3328
	v_mul_f32_e32 v68, 0x4b800000, v88
	v_cndmask_b32_e64 v68, v88, v68, s[36:37]
	v_rsq_f32_e32 v68, v68
	s_waitcnt vmcnt(17)
	v_lshlrev_b32_e32 v93, 16, v137
	v_mul_f32_e32 v69, 0x45800000, v68
	v_cndmask_b32_e64 v68, v68, v69, s[36:37]
	v_mul_f32_e32 v69, v99, v68
	v_mul_f32_e32 v84, v100, v68
	v_mul_f32_e32 v68, v101, v68
	v_mul_f32_e32 v68, v68, v94
	ds_bpermute_b32 v85, v102, v68
	v_mul_f32_e32 v84, v84, v92
	v_cvt_pk_bf16_f32 v84, v84, s0
	v_mul_f32_e32 v69, v69, v95
	global_store_short v[86:87], v84, off offset:3200
	s_waitcnt lgkmcnt(0)
	v_mul_f32_e32 v85, v117, v85
	v_cndmask_b32_e64 v85, v85, -v85, vcc
	v_fmac_f32_e32 v85, v116, v68
	v_cvt_pk_bf16_f32 v84, v85, s0
	v_cvt_pk_bf16_f32 v88, v69, s0
	global_store_short v[86:87], v84, off offset:3328
	v_lshlrev_b32_e32 v85, 16, v135
	v_lshlrev_b32_e32 v84, 16, v134
	s_waitcnt vmcnt(18)
	v_lshlrev_b32_e32 v95, 16, v122
	s_waitcnt vmcnt(17)
	v_lshlrev_b32_e32 v94, 16, v123
	v_lshl_add_u64 v[68:69], v[86:87], 0, s[68:69]
	global_store_short v[86:87], v88, off offset:3072
	v_pk_mul_f32 v[86:87], v[84:85], v[84:85]
	v_pk_mul_f32 v[114:115], v[94:95], v[94:95]
	v_lshlrev_b32_e32 v92, 16, v136
	v_mov_b32_e32 v116, v115
	v_mov_b32_e32 v117, v87
	v_pk_fma_f32 v[116:117], v[92:93], v[92:93], v[116:117]
	v_mov_b32_e32 v115, v86
	v_pk_add_f32 v[86:87], v[114:115], v[116:117]
	ds_bpermute_b32 v115, v102, v87
	ds_bpermute_b32 v114, v102, v86
	v_lshl_add_u64 v[88:89], v[130:131], 0, s[68:69]
	v_lshl_add_u64 v[134:135], v[74:75], 0, s[68:69]
	s_waitcnt lgkmcnt(0)
	v_pk_add_f32 v[86:87], v[86:87], v[114:115]
	ds_bpermute_b32 v115, v103, v87
	ds_bpermute_b32 v114, v103, v86
	s_waitcnt lgkmcnt(0)
	v_pk_add_f32 v[86:87], v[86:87], v[114:115]
	s_waitcnt lgkmcnt(0)
	s_nop 1
	v_add_f32_dpp v86, v86, v86 row_mirror row_mask:0xf bank_mask:0xf
	v_add_f32_dpp v87, v87, v87 row_mirror row_mask:0xf bank_mask:0xf
	s_waitcnt lgkmcnt(0)
	s_nop 1
	v_add_f32_dpp v86, v86, v86 row_half_mirror row_mask:0xf bank_mask:0xf
	v_add_f32_dpp v87, v87, v87 row_half_mirror row_mask:0xf bank_mask:0xf
	s_waitcnt lgkmcnt(0)
	s_nop 1
	v_add_f32_dpp v86, v86, v86 quad_perm:[2,3,0,1] row_mask:0xf bank_mask:0xf
	v_add_f32_dpp v87, v87, v87 quad_perm:[2,3,0,1] row_mask:0xf bank_mask:0xf
	s_waitcnt lgkmcnt(0)
	s_nop 1
	v_add_f32_dpp v86, v86, v86 quad_perm:[1,0,3,2] row_mask:0xf bank_mask:0xf
	v_add_f32_dpp v87, v87, v87 quad_perm:[1,0,3,2] row_mask:0xf bank_mask:0xf
	s_nop 0
	v_pk_fma_f32 v[86:87], v[86:87], s[0:1], v[66:67] op_sel_hi:[1,0,0]
	s_nop 0
	v_mul_f32_e32 v113, 0x4b800000, v87
	v_cmp_gt_f32_e64 s[38:39], s33, v87
	v_cmp_gt_f32_e64 s[36:37], s33, v86
	s_nop 0
	v_cndmask_b32_e64 v87, v87, v113, s[38:39]
	v_rsq_f32_e32 v87, v87
	s_nop 0
	v_mul_f32_e32 v113, 0x45800000, v87
	v_cndmask_b32_e64 v87, v87, v113, s[38:39]
	v_mul_f32_e32 v113, v96, v87
	v_mul_f32_e32 v85, v113, v85
	v_mul_f32_e32 v113, v97, v87
	v_mul_f32_e32 v87, v98, v87
	v_mul_f32_e32 v84, v87, v84
	ds_bpermute_b32 v87, v102, v84
	v_mul_f32_e32 v93, v113, v93
	s_waitcnt lgkmcnt(0)
	v_mul_f32_e32 v87, v79, v87
	v_cndmask_b32_e64 v87, v87, -v87, vcc
	v_fmac_f32_e32 v87, v78, v84
	v_mul_f32_e32 v84, 0x3dd53b94, v85
	v_cvt_pk_bf16_f32 v84, v84, s0
	global_store_short v[130:131], v84, off offset:3072
	v_mul_f32_e32 v84, 0x3dd53b94, v93
	v_cvt_pk_bf16_f32 v84, v84, s0
	global_store_short v[130:131], v84, off offset:3200
	v_mul_f32_e32 v84, 0x3dd53b94, v87
	v_cvt_pk_bf16_f32 v84, v84, s0
	global_store_short v[130:131], v84, off offset:3328
	v_mul_f32_e32 v84, 0x4b800000, v86
	v_cndmask_b32_e64 v84, v86, v84, s[36:37]
	v_rsq_f32_e32 v84, v84
	v_lshl_add_u64 v[130:131], v[128:129], 0, v[188:189]
	v_lshl_add_u64 v[128:129], v[128:129], 0, v[64:65]
	v_mul_f32_e32 v85, 0x45800000, v84
	v_cndmask_b32_e64 v84, v84, v85, s[36:37]
	v_mul_f32_e32 v85, v99, v84
	v_mul_f32_e32 v86, v100, v84
	v_mul_f32_e32 v84, v101, v84
	v_mul_f32_e32 v84, v84, v94
	ds_bpermute_b32 v87, v102, v84
	v_mul_f32_e32 v85, v85, v95
	v_mul_f32_e32 v86, v86, v92
	v_lshl_add_u64 v[92:93], v[70:71], 0, s[68:69]
	v_lshl_add_u64 v[94:95], v[90:91], 0, s[68:69]
	s_waitcnt lgkmcnt(0)
; DI u16 f2bf(float a) { return (u16)(pack2(a, 0.f) & 0xffffu); }
; DI float bf2f(u16 v) { return __uint_as_float(((unsigned)v) << 16); }
; DI float wave_sum(float v) {
; #pragma unroll
;   for (int o = 32; o; o >>= 1) v += __shfl_xor(v, o);
;   return v;
; DI void prep_item(const Params& p, int l, int item) {
;     ...
;       for (int j = 0; j < 4; j++) {
;         const size_t t = tb + t4 + j;
;         csa[j] = rope[(s0 + t4 + j) * 32 + (lane & 31)];
;         const u16* qr = qb + t * 768 + hd * 192;
;         qa[j][0] = qr[lane]; qa[j][1] = qr[64 + lane]; qa[j][2] = qr[128 + lane];
;         const u16* kvr = kvraw + t * 1024 + hd * 256;
;         ka[j][0] = kvr[lane]; ka[j][1] = kvr[64 + lane]; ka[j][2] = z[t * 1760 + 896 + lane];
;         vv[t4 + j] = *(const unsigned*)(kvr + 128 + 2 * lane);
;       }
; #pragma unroll
;       for (int j = 0; j < 4; j++) {
;         const size_t t = tb + t4 + j;
;         const float2 cs = csa[j];
;         u16* qr = qb + t * 768 + hd * 192;
;         float q0 = bf2f(qa[j][0]), q1 = bf2f(qa[j][1]), q2 = bf2f(qa[j][2]);
;         float ss = wave_sum(q0 * q0 + q1 * q1 + q2 * q2);
;         float rs = rsqrtf(ss * (1.f / 192.f) + EPS);
;         q0 *= rs * gq0; q1 *= rs * gq1; q2 *= rs * gq2;
;         float pr = __shfl_xor(q2, 32);
;         float rot = (lane < 32) ? (q2 * cs.x - pr * cs.y) : (q2 * cs.x + pr * cs.y);
;         qr[lane] = f2bf(q0 * QS); qr[64 + lane] = f2bf(q1 * QS); qr[128 + lane] = f2bf(rot * QS);
;         float k0 = bf2f(ka[j][0]), k1 = bf2f(ka[j][1]), k2 = bf2f(ka[j][2]);
;         float ks = wave_sum(k0 * k0 + k1 * k1 + k2 * k2);
;         float rk = rsqrtf(ks * (1.f / 192.f) + EPS);
;         k0 *= rk * gk0; k1 *= rk * gk1; k2 *= rk * gk2;
;         float pk = __shfl_xor(k2, 32);
;         float rotk = (lane < 32) ? (k2 * cs.x - pk * cs.y) : (k2 * cs.x + pk * cs.y);
;         u16* kr = kb + t * 768 + hd * 192;
;         kr[lane] = f2bf(k0); kr[64 + lane] = f2bf(k1); kr[128 + lane] = f2bf(rotk);
;       }
	v_mul_f32_e32 v79, v79, v87
	v_cndmask_b32_e64 v79, v79, -v79, vcc
	v_fmac_f32_e32 v79, v78, v84
	v_cvt_pk_bf16_f32 v78, v85, s0
	global_store_short v[70:71], v78, off offset:3072
	v_cvt_pk_bf16_f32 v78, v86, s0
	global_store_short v[70:71], v78, off offset:3200
	v_cvt_pk_bf16_f32 v78, v79, s0
	global_store_short v[70:71], v78, off offset:3328
	s_waitcnt vmcnt(22)
	v_lshlrev_b32_e32 v71, 16, v139
	v_lshlrev_b32_e32 v70, 16, v138
	s_waitcnt vmcnt(19)
	v_lshlrev_b32_e32 v87, 16, v126
	s_waitcnt vmcnt(18)
	v_lshlrev_b32_e32 v86, 16, v127
	v_pk_mul_f32 v[78:79], v[70:71], v[70:71]
	v_pk_mul_f32 v[114:115], v[86:87], v[86:87]
	v_lshlrev_b32_e32 v85, 16, v141
	v_lshlrev_b32_e32 v84, 16, v140
	v_mov_b32_e32 v116, v115
	v_mov_b32_e32 v117, v79
	v_pk_fma_f32 v[116:117], v[84:85], v[84:85], v[116:117]
	v_mov_b32_e32 v115, v78
	v_pk_add_f32 v[78:79], v[114:115], v[116:117]
	ds_bpermute_b32 v115, v102, v79
	ds_bpermute_b32 v114, v102, v78
	v_lshl_add_u64 v[116:117], v[88:89], 0, s[68:69]
	v_lshl_add_u64 v[122:123], v[94:95], 0, s[68:69]
	s_waitcnt lgkmcnt(0)
	v_pk_add_f32 v[78:79], v[78:79], v[114:115]
	ds_bpermute_b32 v115, v103, v79
	ds_bpermute_b32 v114, v103, v78
	s_waitcnt lgkmcnt(0)
	v_pk_add_f32 v[78:79], v[78:79], v[114:115]
	s_waitcnt lgkmcnt(0)
	s_nop 1
	v_add_f32_dpp v78, v78, v78 row_mirror row_mask:0xf bank_mask:0xf
	v_add_f32_dpp v79, v79, v79 row_mirror row_mask:0xf bank_mask:0xf
	s_waitcnt lgkmcnt(0)
	s_nop 1
	v_add_f32_dpp v78, v78, v78 row_half_mirror row_mask:0xf bank_mask:0xf
	v_add_f32_dpp v79, v79, v79 row_half_mirror row_mask:0xf bank_mask:0xf
	s_waitcnt lgkmcnt(0)
	s_nop 1
	v_add_f32_dpp v78, v78, v78 quad_perm:[2,3,0,1] row_mask:0xf bank_mask:0xf
	v_add_f32_dpp v79, v79, v79 quad_perm:[2,3,0,1] row_mask:0xf bank_mask:0xf
	s_waitcnt lgkmcnt(0)
	s_nop 1
	v_add_f32_dpp v78, v78, v78 quad_perm:[1,0,3,2] row_mask:0xf bank_mask:0xf
	v_add_f32_dpp v79, v79, v79 quad_perm:[1,0,3,2] row_mask:0xf bank_mask:0xf
	s_nop 0
	v_pk_fma_f32 v[78:79], v[78:79], s[0:1], v[66:67] op_sel_hi:[1,0,0]
	s_nop 0
	v_mul_f32_e32 v113, 0x4b800000, v79
	v_cmp_gt_f32_e64 s[38:39], s33, v79
	v_cmp_gt_f32_e64 s[36:37], s33, v78
	s_nop 0
	v_cndmask_b32_e64 v79, v79, v113, s[38:39]
	v_rsq_f32_e32 v79, v79
	s_nop 0
	v_mul_f32_e32 v113, 0x45800000, v79
	v_cndmask_b32_e64 v79, v79, v113, s[38:39]
	v_mul_f32_e32 v113, v96, v79
	v_mul_f32_e32 v71, v113, v71
	v_mul_f32_e32 v113, v97, v79
	v_mul_f32_e32 v79, v98, v79
	v_mul_f32_e32 v70, v79, v70
	ds_bpermute_b32 v79, v102, v70
	v_mul_f32_e32 v85, v113, v85
	s_waitcnt lgkmcnt(0)
	v_mul_f32_e32 v79, v77, v79
	v_cndmask_b32_e64 v79, v79, -v79, vcc
	v_fmac_f32_e32 v79, v76, v70
	v_mul_f32_e32 v70, 0x3dd53b94, v71
	v_cvt_pk_bf16_f32 v70, v70, s0
	global_store_short v[90:91], v70, off offset:3072
	v_mul_f32_e32 v70, 0x3dd53b94, v85
	v_cvt_pk_bf16_f32 v70, v70, s0
	global_store_short v[90:91], v70, off offset:3200
	v_mul_f32_e32 v70, 0x3dd53b94, v79
	v_cvt_pk_bf16_f32 v70, v70, s0
	global_store_short v[90:91], v70, off offset:3328
	v_mul_f32_e32 v70, 0x4b800000, v78
	v_cndmask_b32_e64 v70, v78, v70, s[36:37]
	v_rsq_f32_e32 v70, v70
	v_lshl_add_u64 v[90:91], v[68:69], 0, s[68:69]
	v_mul_f32_e32 v71, 0x45800000, v70
	v_cndmask_b32_e64 v70, v70, v71, s[36:37]
	v_mul_f32_e32 v71, v99, v70
	v_mul_f32_e32 v78, v100, v70
	v_mul_f32_e32 v70, v101, v70
	v_mul_f32_e32 v70, v70, v86
	ds_bpermute_b32 v79, v102, v70
	v_mul_f32_e32 v71, v71, v87
	v_mul_f32_e32 v78, v78, v84
	s_waitcnt lgkmcnt(0)
	v_mul_f32_e32 v77, v77, v79
	v_cndmask_b32_e64 v77, v77, -v77, vcc
	v_fmac_f32_e32 v77, v76, v70
	v_cvt_pk_bf16_f32 v70, v71, s0
	global_store_short v[68:69], v70, off offset:3072
	v_cvt_pk_bf16_f32 v70, v78, s0
	global_store_short v[68:69], v70, off offset:3200
	v_cvt_pk_bf16_f32 v70, v77, s0
	global_store_short v[68:69], v70, off offset:3328
	v_lshl_add_u64 v[68:69], s[26:27], 0, v[30:31]
	v_lshl_add_u64 v[118:119], v[68:69], 0, v[188:189]
	v_lshl_add_u64 v[68:69], v[68:69], 0, v[64:65]
	global_load_dwordx2 v[114:115], v[0:1], off offset:2048
	global_load_dword v84, v[68:69], off offset:256
	global_load_dwordx2 v[120:121], v[0:1], off offset:2304
	v_lshl_add_u64 v[68:69], s[26:27], 0, v[34:35]
	v_lshl_add_u64 v[124:125], v[68:69], 0, v[188:189]
	v_lshl_add_u64 v[68:69], v[68:69], 0, v[64:65]
	global_load_dword v85, v[68:69], off offset:256
	global_load_dwordx2 v[78:79], v[0:1], off offset:2560
	v_lshl_add_u64 v[68:69], s[26:27], 0, v[36:37]
	v_lshl_add_u64 v[126:127], v[68:69], 0, v[188:189]
	v_lshl_add_u64 v[68:69], v[68:69], 0, v[64:65]
	global_load_dword v86, v[68:69], off offset:256
	global_load_dwordx2 v[76:77], v[0:1], off offset:2816
	global_load_dword v87, v[128:129], off offset:256
	global_load_ushort v113, v[88:89], off offset:3328
	s_nop 0
	global_load_ushort v128, v[88:89], off offset:3072
	v_lshl_add_u64 v[70:71], v[116:117], 0, s[68:69]
	v_lshl_add_u64 v[68:69], v[122:123], 0, s[68:69]
	s_waitcnt vmcnt(0)
	v_lshlrev_b32_e32 v129, 16, v128
	v_lshlrev_b32_e32 v128, 16, v113
	global_load_ushort v113, v[118:119], off offset:128
	s_nop 0
	global_load_ushort v88, v[88:89], off offset:3200
	v_pk_mul_f32 v[132:133], v[128:129], v[128:129]
	s_waitcnt vmcnt(0)
	v_lshlrev_b32_e32 v89, 16, v88
	v_lshlrev_b32_e32 v88, 16, v113
	global_load_ushort v113, v[118:119], off
	s_nop 0
	global_load_ushort v118, v[32:33], off
	v_mov_b32_e32 v139, v133
	s_waitcnt vmcnt(1)
	v_lshlrev_b32_e32 v119, 16, v113
	s_waitcnt vmcnt(0)
	v_lshlrev_b32_e32 v118, 16, v118
	v_pk_mul_f32 v[136:137], v[118:119], v[118:119]
	s_nop 0
	v_mov_b32_e32 v138, v137
	v_pk_fma_f32 v[138:139], v[88:89], v[88:89], v[138:139]
	v_mov_b32_e32 v137, v132
	v_pk_add_f32 v[132:133], v[136:137], v[138:139]
	ds_bpermute_b32 v137, v102, v133
	ds_bpermute_b32 v136, v102, v132
	s_waitcnt lgkmcnt(0)
; DI u16 f2bf(float a) { return (u16)(pack2(a, 0.f) & 0xffffu); }
; DI float bf2f(u16 v) { return __uint_as_float(((unsigned)v) << 16); }
; DI float wave_sum(float v) {
; #pragma unroll
;   for (int o = 32; o; o >>= 1) v += __shfl_xor(v, o);
;   return v;
; DI void prep_item(const Params& p, int l, int item) {
;     ...
;       for (int j = 0; j < 4; j++) {
;         const size_t t = tb + t4 + j;
;         csa[j] = rope[(s0 + t4 + j) * 32 + (lane & 31)];
;         const u16* qr = qb + t * 768 + hd * 192;
;         qa[j][0] = qr[lane]; qa[j][1] = qr[64 + lane]; qa[j][2] = qr[128 + lane];
;         const u16* kvr = kvraw + t * 1024 + hd * 256;
;         ka[j][0] = kvr[lane]; ka[j][1] = kvr[64 + lane]; ka[j][2] = z[t * 1760 + 896 + lane];
;         vv[t4 + j] = *(const unsigned*)(kvr + 128 + 2 * lane);
;       }
; #pragma unroll
;       for (int j = 0; j < 4; j++) {
;         const size_t t = tb + t4 + j;
;         const float2 cs = csa[j];
;         u16* qr = qb + t * 768 + hd * 192;
;         float q0 = bf2f(qa[j][0]), q1 = bf2f(qa[j][1]), q2 = bf2f(qa[j][2]);
;         float ss = wave_sum(q0 * q0 + q1 * q1 + q2 * q2);
;         float rs = rsqrtf(ss * (1.f / 192.f) + EPS);
;         q0 *= rs * gq0; q1 *= rs * gq1; q2 *= rs * gq2;
;         float pr = __shfl_xor(q2, 32);
;         float rot = (lane < 32) ? (q2 * cs.x - pr * cs.y) : (q2 * cs.x + pr * cs.y);
;         qr[lane] = f2bf(q0 * QS); qr[64 + lane] = f2bf(q1 * QS); qr[128 + lane] = f2bf(rot * QS);
;         float k0 = bf2f(ka[j][0]), k1 = bf2f(ka[j][1]), k2 = bf2f(ka[j][2]);
;         float ks = wave_sum(k0 * k0 + k1 * k1 + k2 * k2);
;         float rk = rsqrtf(ks * (1.f / 192.f) + EPS);
;         k0 *= rk * gk0; k1 *= rk * gk1; k2 *= rk * gk2;
;         float pk = __shfl_xor(k2, 32);
;         float rotk = (lane < 32) ? (k2 * cs.x - pk * cs.y) : (k2 * cs.x + pk * cs.y);
;         u16* kr = kb + t * 768 + hd * 192;
;         kr[lane] = f2bf(k0); kr[64 + lane] = f2bf(k1); kr[128 + lane] = f2bf(rotk);
;       }
	v_pk_add_f32 v[132:133], v[132:133], v[136:137]
	ds_bpermute_b32 v137, v103, v133
	ds_bpermute_b32 v136, v103, v132
	s_waitcnt lgkmcnt(0)
	v_pk_add_f32 v[132:133], v[132:133], v[136:137]
	s_waitcnt lgkmcnt(0)
	s_nop 1
	v_add_f32_dpp v132, v132, v132 row_mirror row_mask:0xf bank_mask:0xf
	v_add_f32_dpp v133, v133, v133 row_mirror row_mask:0xf bank_mask:0xf
	s_waitcnt lgkmcnt(0)
	s_nop 1
	v_add_f32_dpp v132, v132, v132 row_half_mirror row_mask:0xf bank_mask:0xf
	v_add_f32_dpp v133, v133, v133 row_half_mirror row_mask:0xf bank_mask:0xf
	s_waitcnt lgkmcnt(0)
	s_nop 1
	v_add_f32_dpp v132, v132, v132 quad_perm:[2,3,0,1] row_mask:0xf bank_mask:0xf
	v_add_f32_dpp v133, v133, v133 quad_perm:[2,3,0,1] row_mask:0xf bank_mask:0xf
	s_waitcnt lgkmcnt(0)
	s_nop 1
	v_add_f32_dpp v132, v132, v132 quad_perm:[1,0,3,2] row_mask:0xf bank_mask:0xf
	v_add_f32_dpp v133, v133, v133 quad_perm:[1,0,3,2] row_mask:0xf bank_mask:0xf
	s_nop 0
	v_pk_fma_f32 v[132:133], v[132:133], s[0:1], v[66:67] op_sel_hi:[1,0,0]
	s_nop 0
	v_mul_f32_e32 v113, 0x4b800000, v133
	v_cmp_gt_f32_e64 s[38:39], s33, v133
	v_cmp_gt_f32_e64 s[36:37], s33, v132
	s_nop 0
	v_cndmask_b32_e64 v113, v133, v113, s[38:39]
	v_rsq_f32_e32 v113, v113
	s_nop 0
	v_mul_f32_e32 v133, 0x45800000, v113
	v_cndmask_b32_e64 v113, v113, v133, s[38:39]
	v_mul_f32_e32 v133, v96, v113
	v_mul_f32_e32 v129, v133, v129
	v_mul_f32_e32 v133, v97, v113
	v_mul_f32_e32 v113, v98, v113
	v_mul_f32_e32 v113, v113, v128
	ds_bpermute_b32 v128, v102, v113
	v_mul_f32_e32 v89, v133, v89
	v_mul_f32_e32 v89, 0x3dd53b94, v89
	v_cvt_pk_bf16_f32 v89, v89, s0
	s_waitcnt lgkmcnt(0)
	v_mul_f32_e32 v128, v115, v128
	v_cndmask_b32_e64 v128, v128, -v128, vcc
	v_fmac_f32_e32 v128, v114, v113
	v_mul_f32_e32 v113, 0x3dd53b94, v129
	global_load_ushort v129, v[94:95], off offset:3328
	global_load_ushort v133, v[94:95], off offset:3072
	global_load_ushort v136, v[124:125], off offset:128
	global_load_ushort v137, v[94:95], off offset:3200
	s_nop 0
	global_load_ushort v124, v[124:125], off
	s_nop 0
	global_load_ushort v125, v[32:33], off offset:3520
	global_load_ushort v138, v[116:117], off offset:3328
	global_load_ushort v139, v[116:117], off offset:3072
	global_load_ushort v140, v[126:127], off offset:128
	global_load_ushort v141, v[116:117], off offset:3200
	s_nop 0
	global_load_ushort v126, v[126:127], off
	s_nop 0
	global_load_ushort v127, v[38:39], off
	global_load_ushort v142, v[122:123], off offset:3328
	global_load_ushort v143, v[122:123], off offset:3072
	global_load_ushort v144, v[130:131], off offset:128
	global_load_ushort v145, v[122:123], off offset:3200
	s_nop 0
	global_load_ushort v130, v[130:131], off
	s_nop 0
	global_load_ushort v131, v[42:43], off
	v_cvt_pk_bf16_f32 v113, v113, s0
	global_store_short v[74:75], v89, off offset:3200
	v_mul_f32_e32 v89, 0x3dd53b94, v128
	v_cvt_pk_bf16_f32 v89, v89, s0
	global_store_short v[74:75], v113, off offset:3072
	global_store_short v[74:75], v89, off offset:3328
	v_mul_f32_e32 v74, 0x4b800000, v132
	v_cndmask_b32_e64 v74, v132, v74, s[36:37]
	v_rsq_f32_e32 v74, v74
	s_waitcnt vmcnt(16)
	v_lshlrev_b32_e32 v117, 16, v124
	v_mul_f32_e32 v75, 0x45800000, v74
	v_cndmask_b32_e64 v74, v74, v75, s[36:37]
	v_mul_f32_e32 v75, v99, v74
	v_mul_f32_e32 v89, v100, v74
	v_mul_f32_e32 v74, v101, v74
	v_mul_f32_e32 v74, v74, v118
	v_mul_f32_e32 v88, v89, v88
	ds_bpermute_b32 v89, v102, v74
	v_cvt_pk_bf16_f32 v88, v88, s0
	v_mul_f32_e32 v75, v75, v119
	global_store_short v[92:93], v88, off offset:3200
	v_cvt_pk_bf16_f32 v94, v75, s0
	s_waitcnt lgkmcnt(0)
	v_mul_f32_e32 v89, v115, v89
	v_cndmask_b32_e64 v89, v89, -v89, vcc
	v_fmac_f32_e32 v89, v114, v74
	v_cvt_pk_bf16_f32 v88, v89, s0
	global_store_short v[92:93], v88, off offset:3328
	v_lshlrev_b32_e32 v89, 16, v133
	v_lshlrev_b32_e32 v88, 16, v129
	s_waitcnt vmcnt(17)
	v_lshlrev_b32_e32 v116, 16, v125
	v_lshl_add_u64 v[74:75], v[92:93], 0, s[68:69]
	global_store_short v[92:93], v94, off offset:3072
	v_pk_mul_f32 v[92:93], v[88:89], v[88:89]
	v_pk_mul_f32 v[118:119], v[116:117], v[116:117]
	v_lshlrev_b32_e32 v115, 16, v137
	v_lshlrev_b32_e32 v114, 16, v136
	v_mov_b32_e32 v122, v119
	v_mov_b32_e32 v123, v93
	v_pk_fma_f32 v[122:123], v[114:115], v[114:115], v[122:123]
	v_mov_b32_e32 v119, v92
	v_pk_add_f32 v[92:93], v[118:119], v[122:123]
	ds_bpermute_b32 v119, v102, v93
	ds_bpermute_b32 v118, v102, v92
	v_lshl_add_u64 v[94:95], v[72:73], 0, s[68:69]
	v_lshl_add_u64 v[128:129], s[26:27], 0, v[56:57]
	s_waitcnt lgkmcnt(0)
	v_pk_add_f32 v[92:93], v[92:93], v[118:119]
	ds_bpermute_b32 v119, v103, v93
	ds_bpermute_b32 v118, v103, v92
	s_waitcnt lgkmcnt(0)
	v_pk_add_f32 v[92:93], v[92:93], v[118:119]
	s_waitcnt lgkmcnt(0)
	s_nop 1
	v_add_f32_dpp v92, v92, v92 row_mirror row_mask:0xf bank_mask:0xf
	v_add_f32_dpp v93, v93, v93 row_mirror row_mask:0xf bank_mask:0xf
	s_waitcnt lgkmcnt(0)
	s_nop 1
	v_add_f32_dpp v92, v92, v92 row_half_mirror row_mask:0xf bank_mask:0xf
	v_add_f32_dpp v93, v93, v93 row_half_mirror row_mask:0xf bank_mask:0xf
	s_waitcnt lgkmcnt(0)
	s_nop 1
	v_add_f32_dpp v92, v92, v92 quad_perm:[2,3,0,1] row_mask:0xf bank_mask:0xf
	v_add_f32_dpp v93, v93, v93 quad_perm:[2,3,0,1] row_mask:0xf bank_mask:0xf
	s_waitcnt lgkmcnt(0)
	s_nop 1
	v_add_f32_dpp v92, v92, v92 quad_perm:[1,0,3,2] row_mask:0xf bank_mask:0xf
	v_add_f32_dpp v93, v93, v93 quad_perm:[1,0,3,2] row_mask:0xf bank_mask:0xf
	s_nop 0
	v_pk_fma_f32 v[92:93], v[92:93], s[0:1], v[66:67] op_sel_hi:[1,0,0]
	s_nop 0
	v_mul_f32_e32 v113, 0x4b800000, v93
	v_cmp_gt_f32_e64 s[38:39], s33, v93
	v_cmp_gt_f32_e64 s[36:37], s33, v92
	s_nop 0
	v_cndmask_b32_e64 v93, v93, v113, s[38:39]
	v_rsq_f32_e32 v93, v93
	s_nop 0
	v_mul_f32_e32 v113, 0x45800000, v93
	v_cndmask_b32_e64 v93, v93, v113, s[38:39]
	v_mul_f32_e32 v113, v96, v93
	v_mul_f32_e32 v89, v113, v89
	v_mul_f32_e32 v113, v97, v93
	v_mul_f32_e32 v93, v98, v93
	v_mul_f32_e32 v88, v93, v88
	ds_bpermute_b32 v93, v102, v88
	v_mul_f32_e32 v113, v113, v115
	s_waitcnt vmcnt(14)
; DI u16 f2bf(float a) { return (u16)(pack2(a, 0.f) & 0xffffu); }
; DI float bf2f(u16 v) { return __uint_as_float(((unsigned)v) << 16); }
; DI float wave_sum(float v) {
; #pragma unroll
;   for (int o = 32; o; o >>= 1) v += __shfl_xor(v, o);
;   return v;
; DI void prep_item(const Params& p, int l, int item) {
;     ...
;       for (int j = 0; j < 4; j++) {
;         const size_t t = tb + t4 + j;
;         csa[j] = rope[(s0 + t4 + j) * 32 + (lane & 31)];
;         const u16* qr = qb + t * 768 + hd * 192;
;         qa[j][0] = qr[lane]; qa[j][1] = qr[64 + lane]; qa[j][2] = qr[128 + lane];
;         const u16* kvr = kvraw + t * 1024 + hd * 256;
;         ka[j][0] = kvr[lane]; ka[j][1] = kvr[64 + lane]; ka[j][2] = z[t * 1760 + 896 + lane];
;         vv[t4 + j] = *(const unsigned*)(kvr + 128 + 2 * lane);
;       }
; #pragma unroll
;       for (int j = 0; j < 4; j++) {
;         const size_t t = tb + t4 + j;
;         const float2 cs = csa[j];
;         u16* qr = qb + t * 768 + hd * 192;
;         float q0 = bf2f(qa[j][0]), q1 = bf2f(qa[j][1]), q2 = bf2f(qa[j][2]);
;         float ss = wave_sum(q0 * q0 + q1 * q1 + q2 * q2);
;         float rs = rsqrtf(ss * (1.f / 192.f) + EPS);
;         q0 *= rs * gq0; q1 *= rs * gq1; q2 *= rs * gq2;
;         float pr = __shfl_xor(q2, 32);
;         float rot = (lane < 32) ? (q2 * cs.x - pr * cs.y) : (q2 * cs.x + pr * cs.y);
;         qr[lane] = f2bf(q0 * QS); qr[64 + lane] = f2bf(q1 * QS); qr[128 + lane] = f2bf(rot * QS);
;         float k0 = bf2f(ka[j][0]), k1 = bf2f(ka[j][1]), k2 = bf2f(ka[j][2]);
;         float ks = wave_sum(k0 * k0 + k1 * k1 + k2 * k2);
;         float rk = rsqrtf(ks * (1.f / 192.f) + EPS);
;         k0 *= rk * gk0; k1 *= rk * gk1; k2 *= rk * gk2;
;         float pk = __shfl_xor(k2, 32);
;         float rotk = (lane < 32) ? (k2 * cs.x - pk * cs.y) : (k2 * cs.x + pk * cs.y);
;         u16* kr = kb + t * 768 + hd * 192;
;         kr[lane] = f2bf(k0); kr[64 + lane] = f2bf(k1); kr[128 + lane] = f2bf(rotk);
;       }
	v_lshlrev_b32_e32 v115, 16, v141
	s_waitcnt lgkmcnt(0)
	v_mul_f32_e32 v93, v121, v93
	v_cndmask_b32_e64 v93, v93, -v93, vcc
	v_fmac_f32_e32 v93, v120, v88
	v_mul_f32_e32 v88, 0x3dd53b94, v89
	v_cvt_pk_bf16_f32 v88, v88, s0
	global_store_short v[72:73], v88, off offset:3072
	v_mul_f32_e32 v88, 0x3dd53b94, v113
	v_cvt_pk_bf16_f32 v88, v88, s0
	global_store_short v[72:73], v88, off offset:3200
	v_mul_f32_e32 v88, 0x3dd53b94, v93
	v_cvt_pk_bf16_f32 v88, v88, s0
	global_store_short v[72:73], v88, off offset:3328
	v_mul_f32_e32 v72, 0x4b800000, v92
	v_cndmask_b32_e64 v72, v92, v72, s[36:37]
	v_rsq_f32_e32 v72, v72
	s_nop 0
	v_mul_f32_e32 v73, 0x45800000, v72
	v_cndmask_b32_e64 v72, v72, v73, s[36:37]
	v_mul_f32_e32 v73, v99, v72
	v_mul_f32_e32 v88, v100, v72
	v_mul_f32_e32 v72, v101, v72
	v_mul_f32_e32 v72, v72, v116
	ds_bpermute_b32 v89, v102, v72
	v_mul_f32_e32 v88, v88, v114
	v_cvt_pk_bf16_f32 v88, v88, s0
	v_mul_f32_e32 v73, v73, v117
	global_store_short v[90:91], v88, off offset:3200
	s_waitcnt lgkmcnt(0)
	v_mul_f32_e32 v89, v121, v89
	v_cndmask_b32_e64 v89, v89, -v89, vcc
	v_fmac_f32_e32 v89, v120, v72
	v_cvt_pk_bf16_f32 v88, v89, s0
	v_cvt_pk_bf16_f32 v92, v73, s0
	global_store_short v[90:91], v88, off offset:3328
	v_lshlrev_b32_e32 v89, 16, v139
	v_lshlrev_b32_e32 v88, 16, v138
	s_waitcnt vmcnt(18)
	v_lshlrev_b32_e32 v117, 16, v126
	s_waitcnt vmcnt(17)
	v_lshlrev_b32_e32 v116, 16, v127
	v_lshl_add_u64 v[72:73], v[90:91], 0, s[68:69]
	global_store_short v[90:91], v92, off offset:3072
	v_pk_mul_f32 v[90:91], v[88:89], v[88:89]
	v_pk_mul_f32 v[118:119], v[116:117], v[116:117]
	v_lshlrev_b32_e32 v114, 16, v140
	v_mov_b32_e32 v120, v119
	v_mov_b32_e32 v121, v91
	v_pk_fma_f32 v[120:121], v[114:115], v[114:115], v[120:121]
	v_mov_b32_e32 v119, v90
	v_pk_add_f32 v[90:91], v[118:119], v[120:121]
	ds_bpermute_b32 v119, v102, v91
	ds_bpermute_b32 v118, v102, v90
	v_lshl_add_u64 v[92:93], v[134:135], 0, s[68:69]
	s_waitcnt lgkmcnt(0)
	v_pk_add_f32 v[90:91], v[90:91], v[118:119]
	ds_bpermute_b32 v119, v103, v91
	ds_bpermute_b32 v118, v103, v90
	s_waitcnt lgkmcnt(0)
	v_pk_add_f32 v[90:91], v[90:91], v[118:119]
	s_waitcnt lgkmcnt(0)
	s_nop 1
	v_add_f32_dpp v90, v90, v90 row_mirror row_mask:0xf bank_mask:0xf
	v_add_f32_dpp v91, v91, v91 row_mirror row_mask:0xf bank_mask:0xf
	s_waitcnt lgkmcnt(0)
	s_nop 1
	v_add_f32_dpp v90, v90, v90 row_half_mirror row_mask:0xf bank_mask:0xf
	v_add_f32_dpp v91, v91, v91 row_half_mirror row_mask:0xf bank_mask:0xf
	s_waitcnt lgkmcnt(0)
	s_nop 1
	v_add_f32_dpp v90, v90, v90 quad_perm:[2,3,0,1] row_mask:0xf bank_mask:0xf
	v_add_f32_dpp v91, v91, v91 quad_perm:[2,3,0,1] row_mask:0xf bank_mask:0xf
	s_waitcnt lgkmcnt(0)
	s_nop 1
	v_add_f32_dpp v90, v90, v90 quad_perm:[1,0,3,2] row_mask:0xf bank_mask:0xf
	v_add_f32_dpp v91, v91, v91 quad_perm:[1,0,3,2] row_mask:0xf bank_mask:0xf
	s_nop 0
	v_pk_fma_f32 v[90:91], v[90:91], s[0:1], v[66:67] op_sel_hi:[1,0,0]
	s_nop 0
	v_mul_f32_e32 v113, 0x4b800000, v91
	v_cmp_gt_f32_e64 s[38:39], s33, v91
	v_cmp_gt_f32_e64 s[36:37], s33, v90
	s_nop 0
	v_cndmask_b32_e64 v91, v91, v113, s[38:39]
	v_rsq_f32_e32 v91, v91
	s_nop 0
	v_mul_f32_e32 v113, 0x45800000, v91
	v_cndmask_b32_e64 v91, v91, v113, s[38:39]
	v_mul_f32_e32 v113, v96, v91
	v_mul_f32_e32 v89, v113, v89
	v_mul_f32_e32 v113, v97, v91
	v_mul_f32_e32 v91, v98, v91
	v_mul_f32_e32 v88, v91, v88
	ds_bpermute_b32 v91, v102, v88
	v_mul_f32_e32 v113, v113, v115
	s_waitcnt vmcnt(14)
	v_lshlrev_b32_e32 v115, 16, v145
	s_waitcnt lgkmcnt(0)
	v_mul_f32_e32 v91, v79, v91
	v_cndmask_b32_e64 v91, v91, -v91, vcc
	v_fmac_f32_e32 v91, v78, v88
	v_mul_f32_e32 v88, 0x3dd53b94, v89
	v_cvt_pk_bf16_f32 v88, v88, s0
	global_store_short v[134:135], v88, off offset:3072
	v_mul_f32_e32 v88, 0x3dd53b94, v113
	v_cvt_pk_bf16_f32 v88, v88, s0
	global_store_short v[134:135], v88, off offset:3200
	v_mul_f32_e32 v88, 0x3dd53b94, v91
	v_cvt_pk_bf16_f32 v88, v88, s0
	global_store_short v[134:135], v88, off offset:3328
	v_mul_f32_e32 v88, 0x4b800000, v90
	v_cndmask_b32_e64 v88, v90, v88, s[36:37]
	v_rsq_f32_e32 v88, v88
	v_lshl_add_u64 v[134:135], v[70:71], 0, s[68:69]
	v_mul_f32_e32 v89, 0x45800000, v88
	v_cndmask_b32_e64 v88, v88, v89, s[36:37]
	v_mul_f32_e32 v89, v99, v88
	v_mul_f32_e32 v90, v100, v88
	v_mul_f32_e32 v88, v101, v88
	v_mul_f32_e32 v88, v88, v116
	ds_bpermute_b32 v91, v102, v88
	v_mul_f32_e32 v89, v89, v117
	v_mul_f32_e32 v90, v90, v114
	s_waitcnt vmcnt(16)
	v_lshlrev_b32_e32 v117, 16, v130
	s_waitcnt vmcnt(15)
	v_lshlrev_b32_e32 v116, 16, v131
	s_waitcnt lgkmcnt(0)
	v_mul_f32_e32 v79, v79, v91
	v_cndmask_b32_e64 v79, v79, -v79, vcc
	v_fmac_f32_e32 v79, v78, v88
	v_cvt_pk_bf16_f32 v78, v89, s0
	global_store_short v[74:75], v78, off offset:3072
	v_cvt_pk_bf16_f32 v78, v90, s0
	global_store_short v[74:75], v78, off offset:3200
	v_cvt_pk_bf16_f32 v78, v79, s0
	v_lshl_add_u64 v[88:89], v[74:75], 0, s[68:69]
	global_store_short v[74:75], v78, off offset:3328
	v_lshlrev_b32_e32 v75, 16, v143
	v_lshlrev_b32_e32 v74, 16, v142
	v_pk_mul_f32 v[78:79], v[74:75], v[74:75]
	v_pk_mul_f32 v[118:119], v[116:117], v[116:117]
	v_lshlrev_b32_e32 v114, 16, v144
	v_mov_b32_e32 v120, v119
	v_mov_b32_e32 v121, v79
	v_pk_fma_f32 v[120:121], v[114:115], v[114:115], v[120:121]
	v_mov_b32_e32 v119, v78
	v_pk_add_f32 v[78:79], v[118:119], v[120:121]
	ds_bpermute_b32 v119, v102, v79
	ds_bpermute_b32 v118, v102, v78
	v_lshl_add_u64 v[90:91], v[94:95], 0, s[68:69]
	v_lshl_add_u64 v[130:131], v[128:129], 0, v[188:189]
	v_lshl_add_u64 v[128:129], v[128:129], 0, v[64:65]
	v_lshl_add_u64 v[122:123], v[90:91], 0, s[68:69]
	s_waitcnt lgkmcnt(0)
; DI u16 f2bf(float a) { return (u16)(pack2(a, 0.f) & 0xffffu); }
; DI float bf2f(u16 v) { return __uint_as_float(((unsigned)v) << 16); }
; DI float wave_sum(float v) {
; #pragma unroll
;   for (int o = 32; o; o >>= 1) v += __shfl_xor(v, o);
;   return v;
; DI void prep_item(const Params& p, int l, int item) {
;     ...
;       for (int j = 0; j < 4; j++) {
;         const size_t t = tb + t4 + j;
;         csa[j] = rope[(s0 + t4 + j) * 32 + (lane & 31)];
;         const u16* qr = qb + t * 768 + hd * 192;
;         qa[j][0] = qr[lane]; qa[j][1] = qr[64 + lane]; qa[j][2] = qr[128 + lane];
;         const u16* kvr = kvraw + t * 1024 + hd * 256;
;         ka[j][0] = kvr[lane]; ka[j][1] = kvr[64 + lane]; ka[j][2] = z[t * 1760 + 896 + lane];
;         vv[t4 + j] = *(const unsigned*)(kvr + 128 + 2 * lane);
;       }
; #pragma unroll
;       for (int j = 0; j < 4; j++) {
;         const size_t t = tb + t4 + j;
;         const float2 cs = csa[j];
;         u16* qr = qb + t * 768 + hd * 192;
;         float q0 = bf2f(qa[j][0]), q1 = bf2f(qa[j][1]), q2 = bf2f(qa[j][2]);
;         float ss = wave_sum(q0 * q0 + q1 * q1 + q2 * q2);
;         float rs = rsqrtf(ss * (1.f / 192.f) + EPS);
;         q0 *= rs * gq0; q1 *= rs * gq1; q2 *= rs * gq2;
;         float pr = __shfl_xor(q2, 32);
;         float rot = (lane < 32) ? (q2 * cs.x - pr * cs.y) : (q2 * cs.x + pr * cs.y);
;         qr[lane] = f2bf(q0 * QS); qr[64 + lane] = f2bf(q1 * QS); qr[128 + lane] = f2bf(rot * QS);
;         float k0 = bf2f(ka[j][0]), k1 = bf2f(ka[j][1]), k2 = bf2f(ka[j][2]);
;         float ks = wave_sum(k0 * k0 + k1 * k1 + k2 * k2);
;         float rk = rsqrtf(ks * (1.f / 192.f) + EPS);
;         k0 *= rk * gk0; k1 *= rk * gk1; k2 *= rk * gk2;
;         float pk = __shfl_xor(k2, 32);
;         float rotk = (lane < 32) ? (k2 * cs.x - pk * cs.y) : (k2 * cs.x + pk * cs.y);
;         u16* kr = kb + t * 768 + hd * 192;
;         kr[lane] = f2bf(k0); kr[64 + lane] = f2bf(k1); kr[128 + lane] = f2bf(rotk);
;       }
	v_pk_add_f32 v[78:79], v[78:79], v[118:119]
	ds_bpermute_b32 v119, v103, v79
	ds_bpermute_b32 v118, v103, v78
	s_waitcnt lgkmcnt(0)
	v_pk_add_f32 v[78:79], v[78:79], v[118:119]
	s_waitcnt lgkmcnt(0)
	s_nop 1
	v_add_f32_dpp v78, v78, v78 row_mirror row_mask:0xf bank_mask:0xf
	v_add_f32_dpp v79, v79, v79 row_mirror row_mask:0xf bank_mask:0xf
	s_waitcnt lgkmcnt(0)
	s_nop 1
	v_add_f32_dpp v78, v78, v78 row_half_mirror row_mask:0xf bank_mask:0xf
	v_add_f32_dpp v79, v79, v79 row_half_mirror row_mask:0xf bank_mask:0xf
	s_waitcnt lgkmcnt(0)
	s_nop 1
	v_add_f32_dpp v78, v78, v78 quad_perm:[2,3,0,1] row_mask:0xf bank_mask:0xf
	v_add_f32_dpp v79, v79, v79 quad_perm:[2,3,0,1] row_mask:0xf bank_mask:0xf
	s_waitcnt lgkmcnt(0)
	s_nop 1
	v_add_f32_dpp v78, v78, v78 quad_perm:[1,0,3,2] row_mask:0xf bank_mask:0xf
	v_add_f32_dpp v79, v79, v79 quad_perm:[1,0,3,2] row_mask:0xf bank_mask:0xf
	s_nop 0
	v_pk_fma_f32 v[78:79], v[78:79], s[0:1], v[66:67] op_sel_hi:[1,0,0]
	s_nop 0
	v_mul_f32_e32 v113, 0x4b800000, v79
	v_cmp_gt_f32_e64 s[38:39], s33, v79
	v_cmp_gt_f32_e64 s[36:37], s33, v78
	s_nop 0
	v_cndmask_b32_e64 v79, v79, v113, s[38:39]
	v_rsq_f32_e32 v79, v79
	s_nop 0
	v_mul_f32_e32 v113, 0x45800000, v79
	v_cndmask_b32_e64 v79, v79, v113, s[38:39]
	v_mul_f32_e32 v113, v96, v79
	v_mul_f32_e32 v75, v113, v75
	v_mul_f32_e32 v113, v97, v79
	v_mul_f32_e32 v79, v98, v79
	v_mul_f32_e32 v74, v79, v74
	ds_bpermute_b32 v79, v102, v74
	v_mul_f32_e32 v113, v113, v115
	s_waitcnt lgkmcnt(0)
	v_mul_f32_e32 v79, v77, v79
	v_cndmask_b32_e64 v79, v79, -v79, vcc
	v_fmac_f32_e32 v79, v76, v74
	v_mul_f32_e32 v74, 0x3dd53b94, v75
	v_cvt_pk_bf16_f32 v74, v74, s0
	global_store_short v[94:95], v74, off offset:3072
	v_mul_f32_e32 v74, 0x3dd53b94, v113
	v_cvt_pk_bf16_f32 v74, v74, s0
	global_store_short v[94:95], v74, off offset:3200
	v_mul_f32_e32 v74, 0x3dd53b94, v79
	v_cvt_pk_bf16_f32 v74, v74, s0
	global_store_short v[94:95], v74, off offset:3328
	v_mul_f32_e32 v74, 0x4b800000, v78
	v_cndmask_b32_e64 v74, v78, v74, s[36:37]
	v_rsq_f32_e32 v74, v74
	v_lshl_add_u64 v[94:95], v[72:73], 0, s[68:69]
	v_mul_f32_e32 v75, 0x45800000, v74
	v_cndmask_b32_e64 v74, v74, v75, s[36:37]
	v_mul_f32_e32 v75, v99, v74
	v_mul_f32_e32 v78, v100, v74
	v_mul_f32_e32 v74, v101, v74
	v_mul_f32_e32 v74, v74, v116
	ds_bpermute_b32 v79, v102, v74
	v_mul_f32_e32 v75, v75, v117
	v_mul_f32_e32 v78, v78, v114
	v_lshl_add_u64 v[116:117], v[92:93], 0, s[68:69]
	s_waitcnt lgkmcnt(0)
	v_mul_f32_e32 v77, v77, v79
	v_cndmask_b32_e64 v77, v77, -v77, vcc
	v_fmac_f32_e32 v77, v76, v74
	v_cvt_pk_bf16_f32 v74, v75, s0
	global_store_short v[72:73], v74, off offset:3072
	v_cvt_pk_bf16_f32 v74, v78, s0
	global_store_short v[72:73], v74, off offset:3200
	v_cvt_pk_bf16_f32 v74, v77, s0
	global_store_short v[72:73], v74, off offset:3328
	v_lshl_add_u64 v[72:73], s[26:27], 0, v[44:45]
	v_lshl_add_u64 v[118:119], v[72:73], 0, v[188:189]
	v_lshl_add_u64 v[72:73], v[72:73], 0, v[64:65]
	global_load_dwordx2 v[114:115], v[0:1], off offset:3072
	global_load_dword v76, v[72:73], off offset:256
	global_load_dwordx2 v[120:121], v[0:1], off offset:3328
	v_lshl_add_u64 v[72:73], s[26:27], 0, v[48:49]
	v_lshl_add_u64 v[124:125], v[72:73], 0, v[188:189]
	v_lshl_add_u64 v[72:73], v[72:73], 0, v[64:65]
	global_load_dword v77, v[72:73], off offset:256
	global_load_dwordx2 v[74:75], v[0:1], off offset:3584
	v_lshl_add_u64 v[72:73], s[26:27], 0, v[52:53]
	v_lshl_add_u64 v[126:127], v[72:73], 0, v[188:189]
	v_lshl_add_u64 v[72:73], v[72:73], 0, v[64:65]
	global_load_dword v78, v[72:73], off offset:256
	s_nop 0
	global_load_dwordx2 v[72:73], v[0:1], off offset:3840
	global_load_dword v65, v[128:129], off offset:256
	global_load_ushort v79, v[92:93], off offset:3328
	global_load_ushort v113, v[92:93], off offset:3072
	s_waitcnt vmcnt(1)
	v_lshlrev_b32_e32 v128, 16, v79
	global_load_ushort v79, v[118:119], off offset:128
	s_nop 0
	global_load_ushort v92, v[92:93], off offset:3200
	s_waitcnt vmcnt(2)
	v_lshlrev_b32_e32 v129, 16, v113
	v_pk_mul_f32 v[132:133], v[128:129], v[128:129]
	s_waitcnt vmcnt(0)
	v_lshlrev_b32_e32 v93, 16, v92
	v_lshlrev_b32_e32 v92, 16, v79
	global_load_ushort v79, v[118:119], off
	global_load_ushort v113, v[46:47], off
	v_mov_b32_e32 v139, v133
	s_waitcnt vmcnt(1)
	v_lshlrev_b32_e32 v119, 16, v79
	s_waitcnt vmcnt(0)
	v_lshlrev_b32_e32 v118, 16, v113
	v_pk_mul_f32 v[136:137], v[118:119], v[118:119]
	s_nop 0
	v_mov_b32_e32 v138, v137
	v_pk_fma_f32 v[138:139], v[92:93], v[92:93], v[138:139]
	v_mov_b32_e32 v137, v132
	v_pk_add_f32 v[132:133], v[136:137], v[138:139]
	ds_bpermute_b32 v137, v102, v133
	ds_bpermute_b32 v136, v102, v132
	s_waitcnt lgkmcnt(0)
	v_pk_add_f32 v[132:133], v[132:133], v[136:137]
	ds_bpermute_b32 v137, v103, v133
	ds_bpermute_b32 v136, v103, v132
	s_waitcnt lgkmcnt(0)
	v_pk_add_f32 v[132:133], v[132:133], v[136:137]
	s_waitcnt lgkmcnt(0)
	s_nop 1
	v_add_f32_dpp v132, v132, v132 row_mirror row_mask:0xf bank_mask:0xf
	v_add_f32_dpp v133, v133, v133 row_mirror row_mask:0xf bank_mask:0xf
	s_waitcnt lgkmcnt(0)
	s_nop 1
	v_add_f32_dpp v132, v132, v132 row_half_mirror row_mask:0xf bank_mask:0xf
	v_add_f32_dpp v133, v133, v133 row_half_mirror row_mask:0xf bank_mask:0xf
	s_waitcnt lgkmcnt(0)
	s_nop 1
	v_add_f32_dpp v132, v132, v132 quad_perm:[2,3,0,1] row_mask:0xf bank_mask:0xf
	v_add_f32_dpp v133, v133, v133 quad_perm:[2,3,0,1] row_mask:0xf bank_mask:0xf
	s_waitcnt lgkmcnt(0)
; DI u16 f2bf(float a) { return (u16)(pack2(a, 0.f) & 0xffffu); }
; DI float bf2f(u16 v) { return __uint_as_float(((unsigned)v) << 16); }
; DI float wave_sum(float v) {
; #pragma unroll
;   for (int o = 32; o; o >>= 1) v += __shfl_xor(v, o);
;   return v;
; DI void prep_item(const Params& p, int l, int item) {
;     ...
;       for (int j = 0; j < 4; j++) {
;         const size_t t = tb + t4 + j;
;         csa[j] = rope[(s0 + t4 + j) * 32 + (lane & 31)];
;         const u16* qr = qb + t * 768 + hd * 192;
;         qa[j][0] = qr[lane]; qa[j][1] = qr[64 + lane]; qa[j][2] = qr[128 + lane];
;         const u16* kvr = kvraw + t * 1024 + hd * 256;
;         ka[j][0] = kvr[lane]; ka[j][1] = kvr[64 + lane]; ka[j][2] = z[t * 1760 + 896 + lane];
;         vv[t4 + j] = *(const unsigned*)(kvr + 128 + 2 * lane);
;       }
; #pragma unroll
;       for (int j = 0; j < 4; j++) {
;         const size_t t = tb + t4 + j;
;         const float2 cs = csa[j];
;         u16* qr = qb + t * 768 + hd * 192;
;         float q0 = bf2f(qa[j][0]), q1 = bf2f(qa[j][1]), q2 = bf2f(qa[j][2]);
;         float ss = wave_sum(q0 * q0 + q1 * q1 + q2 * q2);
;         float rs = rsqrtf(ss * (1.f / 192.f) + EPS);
;         q0 *= rs * gq0; q1 *= rs * gq1; q2 *= rs * gq2;
;         float pr = __shfl_xor(q2, 32);
;         float rot = (lane < 32) ? (q2 * cs.x - pr * cs.y) : (q2 * cs.x + pr * cs.y);
;         qr[lane] = f2bf(q0 * QS); qr[64 + lane] = f2bf(q1 * QS); qr[128 + lane] = f2bf(rot * QS);
;         float k0 = bf2f(ka[j][0]), k1 = bf2f(ka[j][1]), k2 = bf2f(ka[j][2]);
;         float ks = wave_sum(k0 * k0 + k1 * k1 + k2 * k2);
;         float rk = rsqrtf(ks * (1.f / 192.f) + EPS);
;         k0 *= rk * gk0; k1 *= rk * gk1; k2 *= rk * gk2;
;         float pk = __shfl_xor(k2, 32);
;         float rotk = (lane < 32) ? (k2 * cs.x - pk * cs.y) : (k2 * cs.x + pk * cs.y);
;         u16* kr = kb + t * 768 + hd * 192;
;         kr[lane] = f2bf(k0); kr[64 + lane] = f2bf(k1); kr[128 + lane] = f2bf(rotk);
;       }
	s_nop 1
	v_add_f32_dpp v132, v132, v132 quad_perm:[1,0,3,2] row_mask:0xf bank_mask:0xf
	v_add_f32_dpp v133, v133, v133 quad_perm:[1,0,3,2] row_mask:0xf bank_mask:0xf
	s_nop 0
	v_pk_fma_f32 v[132:133], v[132:133], s[0:1], v[66:67] op_sel_hi:[1,0,0]
	s_nop 0
	v_mul_f32_e32 v79, 0x4b800000, v133
	v_cmp_gt_f32_e64 s[38:39], s33, v133
	v_cmp_gt_f32_e64 s[36:37], s33, v132
	s_nop 0
	v_cndmask_b32_e64 v79, v133, v79, s[38:39]
	v_rsq_f32_e32 v79, v79
	s_nop 0
	v_mul_f32_e32 v113, 0x45800000, v79
	v_cndmask_b32_e64 v79, v79, v113, s[38:39]
	v_mul_f32_e32 v113, v96, v79
	v_mul_f32_e32 v113, v113, v129
	v_mul_f32_e32 v129, v97, v79
	v_mul_f32_e32 v79, v98, v79
	v_mul_f32_e32 v79, v79, v128
	ds_bpermute_b32 v128, v102, v79
	v_mul_f32_e32 v93, v129, v93
	s_waitcnt lgkmcnt(0)
	v_mul_f32_e32 v128, v115, v128
	v_cndmask_b32_e64 v128, v128, -v128, vcc
	v_fmac_f32_e32 v128, v114, v79
	v_mul_f32_e32 v79, 0x3dd53b94, v113
	global_load_ushort v113, v[90:91], off offset:3328
	global_load_ushort v129, v[90:91], off offset:3072
	global_load_ushort v133, v[124:125], off offset:128
	global_load_ushort v136, v[90:91], off offset:3200
	s_nop 0
	global_load_ushort v124, v[124:125], off
	s_nop 0
	global_load_ushort v125, v[50:51], off
	global_load_ushort v137, v[116:117], off offset:3328
	global_load_ushort v138, v[116:117], off offset:3072
	global_load_ushort v139, v[126:127], off offset:128
	global_load_ushort v140, v[116:117], off offset:3200
	s_nop 0
	global_load_ushort v126, v[126:127], off
	s_nop 0
	global_load_ushort v127, v[54:55], off
	global_load_ushort v141, v[122:123], off offset:3328
	global_load_ushort v142, v[122:123], off offset:3072
	global_load_ushort v143, v[130:131], off offset:128
	global_load_ushort v144, v[122:123], off offset:3200
	s_nop 0
	global_load_ushort v130, v[130:131], off
	s_nop 0
	global_load_ushort v131, v[58:59], off
	v_cvt_pk_bf16_f32 v79, v79, s0
	global_store_short v[70:71], v79, off offset:3072
	v_mul_f32_e32 v79, 0x3dd53b94, v93
	v_cvt_pk_bf16_f32 v79, v79, s0
	global_store_short v[70:71], v79, off offset:3200
	v_mul_f32_e32 v79, 0x3dd53b94, v128
	v_cvt_pk_bf16_f32 v79, v79, s0
	global_store_short v[70:71], v79, off offset:3328
	v_mul_f32_e32 v70, 0x4b800000, v132
	v_cndmask_b32_e64 v70, v132, v70, s[36:37]
	v_rsq_f32_e32 v70, v70
	s_waitcnt vmcnt(16)
	v_lshlrev_b32_e32 v117, 16, v124
	v_mul_f32_e32 v71, 0x45800000, v70
	v_cndmask_b32_e64 v70, v70, v71, s[36:37]
	v_mul_f32_e32 v71, v99, v70
	v_mul_f32_e32 v79, v100, v70
	v_mul_f32_e32 v70, v101, v70
	v_mul_f32_e32 v70, v70, v118
	ds_bpermute_b32 v90, v102, v70
	v_mul_f32_e32 v79, v79, v92
	v_mul_f32_e32 v71, v71, v119
	v_cvt_pk_bf16_f32 v79, v79, s0
	v_cvt_pk_bf16_f32 v91, v71, s0
	s_waitcnt lgkmcnt(0)
	v_mul_f32_e32 v90, v115, v90
	v_cndmask_b32_e64 v90, v90, -v90, vcc
	v_fmac_f32_e32 v90, v114, v70
	global_store_short v[88:89], v79, off offset:3200
	v_cvt_pk_bf16_f32 v79, v90, s0
	v_lshl_add_u64 v[70:71], v[88:89], 0, s[68:69]
	global_store_short v[88:89], v91, off offset:3072
	global_store_short v[88:89], v79, off offset:3328
	v_lshlrev_b32_e32 v89, 16, v129
	v_lshlrev_b32_e32 v88, 16, v113
	s_waitcnt vmcnt(18)
	v_lshlrev_b32_e32 v116, 16, v125
	v_pk_mul_f32 v[90:91], v[88:89], v[88:89]
	v_pk_mul_f32 v[118:119], v[116:117], v[116:117]
	v_lshlrev_b32_e32 v115, 16, v136
	v_lshlrev_b32_e32 v114, 16, v133
	v_mov_b32_e32 v122, v119
	v_mov_b32_e32 v123, v91
	v_pk_fma_f32 v[122:123], v[114:115], v[114:115], v[122:123]
	v_mov_b32_e32 v119, v90
	v_pk_add_f32 v[90:91], v[118:119], v[122:123]
	ds_bpermute_b32 v119, v102, v91
	ds_bpermute_b32 v118, v102, v90
	v_lshl_add_u64 v[92:93], v[68:69], 0, s[68:69]
	s_waitcnt lgkmcnt(0)
	v_pk_add_f32 v[90:91], v[90:91], v[118:119]
	ds_bpermute_b32 v119, v103, v91
	ds_bpermute_b32 v118, v103, v90
	s_waitcnt lgkmcnt(0)
	v_pk_add_f32 v[90:91], v[90:91], v[118:119]
	s_waitcnt lgkmcnt(0)
	s_nop 1
	v_add_f32_dpp v90, v90, v90 row_mirror row_mask:0xf bank_mask:0xf
	v_add_f32_dpp v91, v91, v91 row_mirror row_mask:0xf bank_mask:0xf
	s_waitcnt lgkmcnt(0)
	s_nop 1
	v_add_f32_dpp v90, v90, v90 row_half_mirror row_mask:0xf bank_mask:0xf
	v_add_f32_dpp v91, v91, v91 row_half_mirror row_mask:0xf bank_mask:0xf
	s_waitcnt lgkmcnt(0)
	s_nop 1
	v_add_f32_dpp v90, v90, v90 quad_perm:[2,3,0,1] row_mask:0xf bank_mask:0xf
	v_add_f32_dpp v91, v91, v91 quad_perm:[2,3,0,1] row_mask:0xf bank_mask:0xf
	s_waitcnt lgkmcnt(0)
	s_nop 1
	v_add_f32_dpp v90, v90, v90 quad_perm:[1,0,3,2] row_mask:0xf bank_mask:0xf
	v_add_f32_dpp v91, v91, v91 quad_perm:[1,0,3,2] row_mask:0xf bank_mask:0xf
	s_nop 0
	v_pk_fma_f32 v[90:91], v[90:91], s[0:1], v[66:67] op_sel_hi:[1,0,0]
	s_nop 0
	v_mul_f32_e32 v79, 0x4b800000, v91
	v_cmp_gt_f32_e64 s[38:39], s33, v91
	v_cmp_gt_f32_e64 s[36:37], s33, v90
	s_nop 0
	v_cndmask_b32_e64 v79, v91, v79, s[38:39]
	v_rsq_f32_e32 v79, v79
	s_nop 0
	v_mul_f32_e32 v91, 0x45800000, v79
	v_cndmask_b32_e64 v79, v79, v91, s[38:39]
	v_mul_f32_e32 v91, v96, v79
	v_mul_f32_e32 v89, v91, v89
	v_mul_f32_e32 v91, v97, v79
	v_mul_f32_e32 v79, v98, v79
	v_mul_f32_e32 v79, v79, v88
	ds_bpermute_b32 v88, v102, v79
	v_mul_f32_e32 v91, v91, v115
	s_waitcnt vmcnt(13)
	v_lshlrev_b32_e32 v115, 16, v126
	s_waitcnt lgkmcnt(0)
; DI u16 f2bf(float a) { return (u16)(pack2(a, 0.f) & 0xffffu); }
; DI float bf2f(u16 v) { return __uint_as_float(((unsigned)v) << 16); }
; DI float wave_sum(float v) {
; #pragma unroll
;   for (int o = 32; o; o >>= 1) v += __shfl_xor(v, o);
;   return v;
; DI void prep_item(const Params& p, int l, int item) {
;     ...
;       for (int j = 0; j < 4; j++) {
;         const size_t t = tb + t4 + j;
;         csa[j] = rope[(s0 + t4 + j) * 32 + (lane & 31)];
;         const u16* qr = qb + t * 768 + hd * 192;
;         qa[j][0] = qr[lane]; qa[j][1] = qr[64 + lane]; qa[j][2] = qr[128 + lane];
;         const u16* kvr = kvraw + t * 1024 + hd * 256;
;         ka[j][0] = kvr[lane]; ka[j][1] = kvr[64 + lane]; ka[j][2] = z[t * 1760 + 896 + lane];
;         vv[t4 + j] = *(const unsigned*)(kvr + 128 + 2 * lane);
;       }
; #pragma unroll
;       for (int j = 0; j < 4; j++) {
;         const size_t t = tb + t4 + j;
;         const float2 cs = csa[j];
;         u16* qr = qb + t * 768 + hd * 192;
;         float q0 = bf2f(qa[j][0]), q1 = bf2f(qa[j][1]), q2 = bf2f(qa[j][2]);
;         float ss = wave_sum(q0 * q0 + q1 * q1 + q2 * q2);
;         float rs = rsqrtf(ss * (1.f / 192.f) + EPS);
;         q0 *= rs * gq0; q1 *= rs * gq1; q2 *= rs * gq2;
;         float pr = __shfl_xor(q2, 32);
;         float rot = (lane < 32) ? (q2 * cs.x - pr * cs.y) : (q2 * cs.x + pr * cs.y);
;         qr[lane] = f2bf(q0 * QS); qr[64 + lane] = f2bf(q1 * QS); qr[128 + lane] = f2bf(rot * QS);
;         float k0 = bf2f(ka[j][0]), k1 = bf2f(ka[j][1]), k2 = bf2f(ka[j][2]);
;         float ks = wave_sum(k0 * k0 + k1 * k1 + k2 * k2);
;         float rk = rsqrtf(ks * (1.f / 192.f) + EPS);
;         k0 *= rk * gk0; k1 *= rk * gk1; k2 *= rk * gk2;
;         float pk = __shfl_xor(k2, 32);
;         float rotk = (lane < 32) ? (k2 * cs.x - pk * cs.y) : (k2 * cs.x + pk * cs.y);
;         u16* kr = kb + t * 768 + hd * 192;
;         kr[lane] = f2bf(k0); kr[64 + lane] = f2bf(k1); kr[128 + lane] = f2bf(rotk);
;       }
	v_mul_f32_e32 v88, v121, v88
	v_cndmask_b32_e64 v88, v88, -v88, vcc
	v_fmac_f32_e32 v88, v120, v79
	v_mul_f32_e32 v79, 0x3dd53b94, v89
	v_cvt_pk_bf16_f32 v79, v79, s0
	global_store_short v[68:69], v79, off offset:3072
	v_mul_f32_e32 v79, 0x3dd53b94, v91
	v_cvt_pk_bf16_f32 v79, v79, s0
	global_store_short v[68:69], v79, off offset:3200
	v_mul_f32_e32 v79, 0x3dd53b94, v88
	v_cvt_pk_bf16_f32 v79, v79, s0
	global_store_short v[68:69], v79, off offset:3328
	v_mul_f32_e32 v68, 0x4b800000, v90
	v_cndmask_b32_e64 v68, v90, v68, s[36:37]
	v_rsq_f32_e32 v68, v68
	s_nop 0
	v_mul_f32_e32 v69, 0x45800000, v68
	v_cndmask_b32_e64 v68, v68, v69, s[36:37]
	v_mul_f32_e32 v69, v99, v68
	v_mul_f32_e32 v79, v100, v68
	v_mul_f32_e32 v68, v101, v68
	v_mul_f32_e32 v68, v68, v116
	ds_bpermute_b32 v88, v102, v68
	v_mul_f32_e32 v69, v69, v117
	v_mul_f32_e32 v79, v79, v114
	v_cvt_pk_bf16_f32 v89, v69, s0
	v_cvt_pk_bf16_f32 v79, v79, s0
	s_waitcnt lgkmcnt(0)
	v_mul_f32_e32 v88, v121, v88
	v_cndmask_b32_e64 v88, v88, -v88, vcc
	v_fmac_f32_e32 v88, v120, v68
	global_store_short v[94:95], v89, off offset:3072
	global_store_short v[94:95], v79, off offset:3200
	v_cvt_pk_bf16_f32 v79, v88, s0
	v_lshlrev_b32_e32 v89, 16, v138
	v_lshlrev_b32_e32 v88, 16, v137
	s_waitcnt vmcnt(17)
	v_lshlrev_b32_e32 v114, 16, v127
	v_pk_mul_f32 v[90:91], v[88:89], v[88:89]
	v_pk_mul_f32 v[116:117], v[114:115], v[114:115]
	v_lshl_add_u64 v[68:69], v[94:95], 0, s[68:69]
	global_store_short v[94:95], v79, off offset:3328
	v_lshlrev_b32_e32 v95, 16, v140
	v_lshlrev_b32_e32 v94, 16, v139
	v_mov_b32_e32 v118, v117
	v_mov_b32_e32 v119, v91
	v_pk_fma_f32 v[118:119], v[94:95], v[94:95], v[118:119]
	v_mov_b32_e32 v117, v90
	v_pk_add_f32 v[90:91], v[116:117], v[118:119]
	ds_bpermute_b32 v117, v102, v91
	ds_bpermute_b32 v116, v102, v90
	s_waitcnt lgkmcnt(0)
	v_pk_add_f32 v[90:91], v[90:91], v[116:117]
	ds_bpermute_b32 v117, v103, v91
	ds_bpermute_b32 v116, v103, v90
	s_waitcnt lgkmcnt(0)
	v_pk_add_f32 v[90:91], v[90:91], v[116:117]
	s_waitcnt lgkmcnt(0)
	s_nop 1
	v_add_f32_dpp v90, v90, v90 row_mirror row_mask:0xf bank_mask:0xf
	v_add_f32_dpp v91, v91, v91 row_mirror row_mask:0xf bank_mask:0xf
	s_waitcnt lgkmcnt(0)
	s_nop 1
	v_add_f32_dpp v90, v90, v90 row_half_mirror row_mask:0xf bank_mask:0xf
	v_add_f32_dpp v91, v91, v91 row_half_mirror row_mask:0xf bank_mask:0xf
	s_waitcnt lgkmcnt(0)
	s_nop 1
	v_add_f32_dpp v90, v90, v90 quad_perm:[2,3,0,1] row_mask:0xf bank_mask:0xf
	v_add_f32_dpp v91, v91, v91 quad_perm:[2,3,0,1] row_mask:0xf bank_mask:0xf
	s_waitcnt lgkmcnt(0)
	s_nop 1
	v_add_f32_dpp v90, v90, v90 quad_perm:[1,0,3,2] row_mask:0xf bank_mask:0xf
	v_add_f32_dpp v91, v91, v91 quad_perm:[1,0,3,2] row_mask:0xf bank_mask:0xf
	s_nop 0
	v_pk_fma_f32 v[90:91], v[90:91], s[0:1], v[66:67] op_sel_hi:[1,0,0]
	s_nop 0
	v_mul_f32_e32 v79, 0x4b800000, v91
	v_cmp_gt_f32_e64 s[38:39], s33, v91
	v_cmp_gt_f32_e64 s[36:37], s33, v90
	s_nop 0
	v_cndmask_b32_e64 v79, v91, v79, s[38:39]
	v_rsq_f32_e32 v79, v79
	s_nop 0
	v_mul_f32_e32 v91, 0x45800000, v79
	v_cndmask_b32_e64 v79, v79, v91, s[38:39]
	v_mul_f32_e32 v91, v96, v79
	v_mul_f32_e32 v89, v91, v89
	v_mul_f32_e32 v91, v97, v79
	v_mul_f32_e32 v79, v98, v79
	v_mul_f32_e32 v79, v79, v88
	ds_bpermute_b32 v88, v102, v79
	v_mul_f32_e32 v91, v91, v95
	s_waitcnt lgkmcnt(0)
	v_mul_f32_e32 v88, v75, v88
	v_cndmask_b32_e64 v88, v88, -v88, vcc
	v_fmac_f32_e32 v88, v74, v79
	v_mul_f32_e32 v79, 0x3dd53b94, v89
	v_cvt_pk_bf16_f32 v79, v79, s0
	global_store_short v[134:135], v79, off offset:3072
	v_mul_f32_e32 v79, 0x3dd53b94, v91
	v_cvt_pk_bf16_f32 v79, v79, s0
	global_store_short v[134:135], v79, off offset:3200
	v_mul_f32_e32 v79, 0x3dd53b94, v88
	v_cvt_pk_bf16_f32 v79, v79, s0
	global_store_short v[134:135], v79, off offset:3328
	v_mul_f32_e32 v79, 0x4b800000, v90
	v_cndmask_b32_e64 v79, v90, v79, s[36:37]
	v_rsq_f32_e32 v79, v79
	s_waitcnt vmcnt(16)
	v_lshlrev_b32_e32 v91, 16, v130
	v_mul_f32_e32 v88, 0x45800000, v79
	v_cndmask_b32_e64 v79, v79, v88, s[36:37]
	v_mul_f32_e32 v88, v99, v79
	v_mul_f32_e32 v89, v100, v79
	v_mul_f32_e32 v79, v101, v79
	v_mul_f32_e32 v79, v79, v114
	ds_bpermute_b32 v90, v102, v79
	v_mul_f32_e32 v88, v88, v115
	v_mul_f32_e32 v89, v89, v94
	s_waitcnt lgkmcnt(0)
	v_mul_f32_e32 v75, v75, v90
	v_cndmask_b32_e64 v75, v75, -v75, vcc
	v_fmac_f32_e32 v75, v74, v79
	v_cvt_pk_bf16_f32 v74, v88, s0
	global_store_short v[70:71], v74, off offset:3072
	v_cvt_pk_bf16_f32 v74, v89, s0
	global_store_short v[70:71], v74, off offset:3200
	v_cvt_pk_bf16_f32 v74, v75, s0
	global_store_short v[70:71], v74, off offset:3328
	v_lshlrev_b32_e32 v71, 16, v142
	v_lshlrev_b32_e32 v70, 16, v141
	s_waitcnt vmcnt(18)
	v_lshlrev_b32_e32 v90, 16, v131
	v_pk_mul_f32 v[74:75], v[70:71], v[70:71]
	v_pk_mul_f32 v[94:95], v[90:91], v[90:91]
	v_lshlrev_b32_e32 v89, 16, v144
	v_lshlrev_b32_e32 v88, 16, v143
	v_mov_b32_e32 v114, v95
	v_mov_b32_e32 v115, v75
	v_pk_fma_f32 v[114:115], v[88:89], v[88:89], v[114:115]
	v_mov_b32_e32 v95, v74
	v_pk_add_f32 v[74:75], v[94:95], v[114:115]
	ds_bpermute_b32 v95, v102, v75
	ds_bpermute_b32 v94, v102, v74
	s_waitcnt lgkmcnt(0)
	v_pk_add_f32 v[74:75], v[74:75], v[94:95]
	ds_bpermute_b32 v95, v103, v75
	ds_bpermute_b32 v94, v103, v74
	s_waitcnt lgkmcnt(0)
; DI void prep_item(const Params& p, int l, int item) {
;     ...
;       for (int j = 0; j < 4; j++) {
;         const size_t t = tb + t4 + j;
;         csa[j] = rope[(s0 + t4 + j) * 32 + (lane & 31)];
;         const u16* qr = qb + t * 768 + hd * 192;
;         qa[j][0] = qr[lane]; qa[j][1] = qr[64 + lane]; qa[j][2] = qr[128 + lane];
;         const u16* kvr = kvraw + t * 1024 + hd * 256;
;         ka[j][0] = kvr[lane]; ka[j][1] = kvr[64 + lane]; ka[j][2] = z[t * 1760 + 896 + lane];
;         vv[t4 + j] = *(const unsigned*)(kvr + 128 + 2 * lane);
;       }
; #pragma unroll
;       for (int j = 0; j < 4; j++) {
;         const size_t t = tb + t4 + j;
;         const float2 cs = csa[j];
;         u16* qr = qb + t * 768 + hd * 192;
;         float q0 = bf2f(qa[j][0]), q1 = bf2f(qa[j][1]), q2 = bf2f(qa[j][2]);
;         float ss = wave_sum(q0 * q0 + q1 * q1 + q2 * q2);
;         float rs = rsqrtf(ss * (1.f / 192.f) + EPS);
;         q0 *= rs * gq0; q1 *= rs * gq1; q2 *= rs * gq2;
;         float pr = __shfl_xor(q2, 32);
;         float rot = (lane < 32) ? (q2 * cs.x - pr * cs.y) : (q2 * cs.x + pr * cs.y);
;         qr[lane] = f2bf(q0 * QS); qr[64 + lane] = f2bf(q1 * QS); qr[128 + lane] = f2bf(rot * QS);
;         float k0 = bf2f(ka[j][0]), k1 = bf2f(ka[j][1]), k2 = bf2f(ka[j][2]);
;         float ks = wave_sum(k0 * k0 + k1 * k1 + k2 * k2);
;         float rk = rsqrtf(ks * (1.f / 192.f) + EPS);
;         k0 *= rk * gk0; k1 *= rk * gk1; k2 *= rk * gk2;
;         float pk = __shfl_xor(k2, 32);
;         float rotk = (lane < 32) ? (k2 * cs.x - pk * cs.y) : (k2 * cs.x + pk * cs.y);
;         u16* kr = kb + t * 768 + hd * 192;
;         kr[lane] = f2bf(k0); kr[64 + lane] = f2bf(k1); kr[128 + lane] = f2bf(rotk);
;       }
;     }
; #pragma unroll
;     for (int e2 = 0; e2 < 2; e2++) {
;       unsigned o[8];
; #pragma unroll
;       for (int pp = 0; pp < 8; pp++) {
;         const int p0 = 2 * pp, p1 = 2 * pp + 1;
;         const int o0 = ((p0 >> 2) & 1) * 8 + (p0 >> 3) * 4 + (p0 & 3);
;         const int o1 = ((p1 >> 2) & 1) * 8 + (p1 >> 3) * 4 + (p1 & 3);
;         unsigned lo = e2 ? (vv[o0] >> 16) : (vv[o0] & 0xffffu);
;         unsigned hi = e2 ? (vv[o1] >> 16) : (vv[o1] & 0xffffu);
;         o[pp] = lo | (hi << 16);
;       }
;       uint4* dst = (uint4*)(vt + ((size_t)(seq * 4 + hd) * 128 + 2 * lane + e2) * 2048 + s0);
;       dst[0] = make_uint4(o[0], o[1], o[2], o[3]);
	v_pk_add_f32 v[74:75], v[74:75], v[94:95]
	s_waitcnt lgkmcnt(0)
	s_nop 1
	v_add_f32_dpp v74, v74, v74 row_mirror row_mask:0xf bank_mask:0xf
	v_add_f32_dpp v75, v75, v75 row_mirror row_mask:0xf bank_mask:0xf
	s_waitcnt lgkmcnt(0)
	s_nop 1
	v_add_f32_dpp v74, v74, v74 row_half_mirror row_mask:0xf bank_mask:0xf
	v_add_f32_dpp v75, v75, v75 row_half_mirror row_mask:0xf bank_mask:0xf
	s_waitcnt lgkmcnt(0)
	s_nop 1
	v_add_f32_dpp v74, v74, v74 quad_perm:[2,3,0,1] row_mask:0xf bank_mask:0xf
	v_add_f32_dpp v75, v75, v75 quad_perm:[2,3,0,1] row_mask:0xf bank_mask:0xf
	s_waitcnt lgkmcnt(0)
	s_nop 1
	v_add_f32_dpp v74, v74, v74 quad_perm:[1,0,3,2] row_mask:0xf bank_mask:0xf
	v_add_f32_dpp v75, v75, v75 quad_perm:[1,0,3,2] row_mask:0xf bank_mask:0xf
	s_nop 0
	v_pk_fma_f32 v[66:67], v[74:75], s[0:1], v[66:67] op_sel_hi:[1,0,0]
	s_movk_i32 s1, 0x1000
	v_mul_f32_e32 v74, 0x4b800000, v67
	v_cmp_gt_f32_e64 s[38:39], s33, v67
	v_cmp_gt_f32_e64 s[36:37], s33, v66
	s_nop 0
	v_cndmask_b32_e64 v67, v67, v74, s[38:39]
	v_rsq_f32_e32 v67, v67
	s_nop 0
	v_mul_f32_e32 v74, 0x45800000, v67
	v_cndmask_b32_e64 v67, v67, v74, s[38:39]
	v_mul_f32_e32 v74, v96, v67
	v_mul_f32_e32 v71, v74, v71
	v_mul_f32_e32 v74, v97, v67
	v_mul_f32_e32 v67, v98, v67
	v_mul_f32_e32 v67, v67, v70
	ds_bpermute_b32 v70, v102, v67
	v_mul_f32_e32 v74, v74, v89
	s_waitcnt lgkmcnt(0)
	v_mul_f32_e32 v70, v73, v70
	v_cndmask_b32_e64 v70, v70, -v70, vcc
	v_fmac_f32_e32 v70, v72, v67
	v_mul_f32_e32 v67, 0x3dd53b94, v71
	v_cvt_pk_bf16_f32 v67, v67, s0
	global_store_short v[92:93], v67, off offset:3072
	v_mul_f32_e32 v67, 0x3dd53b94, v74
	v_cvt_pk_bf16_f32 v67, v67, s0
	global_store_short v[92:93], v67, off offset:3200
	v_mul_f32_e32 v67, 0x3dd53b94, v70
	v_cvt_pk_bf16_f32 v67, v67, s0
	global_store_short v[92:93], v67, off offset:3328
	v_mul_f32_e32 v67, 0x4b800000, v66
	v_cndmask_b32_e64 v66, v66, v67, s[36:37]
	v_rsq_f32_e32 v66, v66
	s_nop 0
	v_mul_f32_e32 v67, 0x45800000, v66
	v_cndmask_b32_e64 v66, v66, v67, s[36:37]
	v_mul_f32_e32 v67, v99, v66
	v_mul_f32_e32 v70, v100, v66
	v_mul_f32_e32 v66, v101, v66
	v_mul_f32_e32 v66, v66, v90
	ds_bpermute_b32 v71, v102, v66
	v_mul_f32_e32 v67, v67, v91
	v_mul_f32_e32 v70, v70, v88
	s_waitcnt lgkmcnt(0)
	v_mul_f32_e32 v71, v73, v71
	v_cndmask_b32_e64 v71, v71, -v71, vcc
	v_fmac_f32_e32 v71, v72, v66
	v_cvt_pk_bf16_f32 v66, v67, s0
	global_store_short v[68:69], v66, off offset:3072
	v_cvt_pk_bf16_f32 v66, v70, s0
	global_store_short v[68:69], v66, off offset:3200
	v_cvt_pk_bf16_f32 v66, v71, s0
	global_store_short v[68:69], v66, off offset:3328
	v_or_b32_e32 v66, s23, v108
	v_ashrrev_i32_e32 v67, 31, v66
	v_lshlrev_b64 v[66:67], 19, v[66:67]
	v_lshl_add_u64 v[70:71], v[60:61], 0, v[66:67]
	v_lshlrev_b32_e32 v66, 16, v112
	v_lshlrev_b32_e32 v68, 16, v110
	v_or_b32_sdwa v67, v66, v111 dst_sel:DWORD dst_unused:UNUSED_PAD src0_sel:DWORD src1_sel:WORD_0
	v_or_b32_sdwa v66, v68, v109 dst_sel:DWORD dst_unused:UNUSED_PAD src0_sel:DWORD src1_sel:WORD_0
	v_lshlrev_b32_e32 v68, 16, v87
	v_lshlrev_b32_e32 v72, 16, v85
	v_or_b32_sdwa v69, v68, v86 dst_sel:DWORD dst_unused:UNUSED_PAD src0_sel:DWORD src1_sel:WORD_0
	v_or_b32_sdwa v68, v72, v84 dst_sel:DWORD dst_unused:UNUSED_PAD src0_sel:DWORD src1_sel:WORD_0
	global_store_dwordx4 v[70:71], v[66:69], off
	v_lshlrev_b32_e32 v72, 16, v77
	s_add_i32 s23, s23, 1
	v_lshlrev_b32_e32 v66, 16, v83
	v_lshlrev_b32_e32 v68, 16, v81
	v_or_b32_sdwa v67, v66, v82 dst_sel:DWORD dst_unused:UNUSED_PAD src0_sel:DWORD src1_sel:WORD_0
	v_or_b32_sdwa v66, v68, v80 dst_sel:DWORD dst_unused:UNUSED_PAD src0_sel:DWORD src1_sel:WORD_0
	v_lshlrev_b32_e32 v68, 16, v65
	v_or_b32_sdwa v69, v68, v78 dst_sel:DWORD dst_unused:UNUSED_PAD src0_sel:DWORD src1_sel:WORD_0
	v_or_b32_sdwa v68, v72, v76 dst_sel:DWORD dst_unused:UNUSED_PAD src0_sel:DWORD src1_sel:WORD_0
	global_store_dwordx4 v[70:71], v[66:69], off offset:16
	v_and_b32_e32 v72, 0xffff0000, v85
	v_add_co_u32_e64 v70, s[36:37], s1, v70
	v_and_b32_e32 v66, 0xffff0000, v112
	v_and_b32_e32 v68, 0xffff0000, v110
	v_or_b32_sdwa v67, v66, v111 dst_sel:DWORD dst_unused:UNUSED_PAD src0_sel:DWORD src1_sel:WORD_1
	v_or_b32_sdwa v66, v68, v109 dst_sel:DWORD dst_unused:UNUSED_PAD src0_sel:DWORD src1_sel:WORD_1
	v_and_b32_e32 v68, 0xffff0000, v87
	v_or_b32_sdwa v69, v68, v86 dst_sel:DWORD dst_unused:UNUSED_PAD src0_sel:DWORD src1_sel:WORD_1
	v_or_b32_sdwa v68, v72, v84 dst_sel:DWORD dst_unused:UNUSED_PAD src0_sel:DWORD src1_sel:WORD_1
	v_addc_co_u32_e64 v71, s[36:37], 0, v71, s[36:37]
	global_store_dwordx4 v[70:71], v[66:69], off
	v_and_b32_e32 v65, 0xffff0000, v65
	s_cmp_lg_u32 s23, 4
	v_and_b32_e32 v66, 0xffff0000, v83
	v_and_b32_e32 v68, 0xffff0000, v81
	v_or_b32_sdwa v67, v66, v82 dst_sel:DWORD dst_unused:UNUSED_PAD src0_sel:DWORD src1_sel:WORD_1
	v_or_b32_sdwa v66, v68, v80 dst_sel:DWORD dst_unused:UNUSED_PAD src0_sel:DWORD src1_sel:WORD_1
	v_and_b32_e32 v68, 0xffff0000, v77
	v_or_b32_sdwa v69, v65, v78 dst_sel:DWORD dst_unused:UNUSED_PAD src0_sel:DWORD src1_sel:WORD_1
	v_or_b32_sdwa v68, v68, v76 dst_sel:DWORD dst_unused:UNUSED_PAD src0_sel:DWORD src1_sel:WORD_1
	global_store_dwordx4 v[70:71], v[66:69], off offset:16
	s_cbranch_scc1 .LBB0_667
	s_add_i32 s42, s42, s82
	s_cmpk_gt_i32 s42, 0x2ff
	s_cbranch_scc0 .LBB0_666
